# v9 + in-proj GEMM relaxed first-iteration waits (vmcnt 24, gate-tile path drains) + first super-phase LDS reads hoisted to unit header above tile-order scalar code
# speedup vs baseline: 1.0065x; 1.0065x over previous
; #define PG8_STAGE(bufoff, gbase, voff) do { _Pragma("unroll") for (int _i = 0; _i < 2; ++_i) \
;         __builtin_amdgcn_global_load_lds((const unsigned*)((const char*)(gbase) + (voff)[_i]), (PG8_LAS unsigned*)(lds + (bufoff) + ldsw + _i * 8192), 16, 0, 0); } while (0)
; #define PG8_LDA(dst, b, h) do { _Pragma("unroll") for (int m = 0; m < 4; ++m) _Pragma("unroll") for (int k = 0; k < 2; ++k) dst[m][k] = *(const PG8_LAS bf16x8*)(lds + PG8_SA(b, h) + aoff + m * 2048 + k * 1024); } while (0)
; #define PG8_LDB(dst, b, h) do { _Pragma("unroll") for (int n = 0; n < 2; ++n) _Pragma("unroll") for (int k = 0; k < 2; ++k) dst[n][k] = *(const PG8_LAS bf16x8*)(lds + PG8_SB(b, h) + boff + n * 2048 + k * 1024); } while (0)
; #define PG8_SCHED __builtin_amdgcn_sched_barrier(0)
;     __host__ __device__ bool next(int i, Unit& u) const {
;         const long L = (long)i * G + c; if (L >= nwg) return false;
;         int wgid = (int)L; { const int q = nwg / NXCD, r = nwg % NXCD, xcd = wgid % NXCD, off = wgid / NXCD; wgid = (xcd < r ? xcd * (q + 1) : r * (q + 1) + (xcd - r) * q) + off; }
;         const int nig = WGM * nN, gid = wgid / nig, fm = gid * WGM, gsz = (nM - fm) < WGM ? (nM - fm) : WGM;
;         u.pm = fm + ((wgid % nig) % gsz); u.pn = (wgid % nig) / gsz; return true;
;     }
; template <class Epi, class Sched, bool ALIGN_EPI = false, bool SP2 = false>
; __device__ __forceinline__ void gemm_phase(PG8_LAS unsigned char* lds, const Gemm g, const Sched& S, const Epi& E) {
;     ...
;             PG8_LDB(B0, 0, 0); PG8_LDB(B1, 0, 1); PG8_SCHED; PG8_LDA(At, 0, 0); PG8_STAGE(PG8_SA(1, 1), a1 + hstep, voffA);
.LBB0_361:
	v_add_u32_e32 v140, 0x10000, v143
	ds_read_b128 v[154:157], v140
	ds_read_b128 v[158:161], v140 offset:1024
	ds_read_b128 v[162:165], v140 offset:2048
	ds_read_b128 v[166:169], v140 offset:3072
	v_add_u32_e32 v140, 0x14000, v143
	ds_read_b128 v[170:173], v140
	ds_read_b128 v[174:177], v140 offset:1024
	ds_read_b128 v[178:181], v140 offset:2048
	ds_read_b128 v[200:203], v140 offset:3072
	ds_read_b128 v[204:207], v145
	ds_read_b128 v[208:211], v145 offset:1024
	ds_read_b128 v[212:215], v145 offset:2048
	ds_read_b128 v[216:219], v145 offset:3072
	ds_read_b128 v[220:223], v145 offset:4096
	ds_read_b128 v[224:227], v145 offset:5120
	ds_read_b128 v[228:231], v145 offset:6144
	ds_read_b128 v[232:235], v145 offset:7168
	s_add_i32 s31, s31, 1
	s_mul_i32 s4, s31, s79
	s_mul_hi_u32 s5, s31, s78
	s_add_i32 s5, s5, s4
	s_mul_i32 s4, s31, s78
	s_add_u32 s12, s4, s2
	s_addc_u32 s13, s5, s3
	v_mov_b64_e32 v[2:3], 0xfff
	v_cmp_gt_i64_e32 vcc, s[12:13], v[2:3]
	v_cmp_lt_i64_e64 s[4:5], s[12:13], v[190:191]
	s_cbranch_vccnz .LBB0_367
	s_ashr_i32 s8, s12, 31
	s_lshr_b32 s8, s8, 29
	s_add_i32 s10, s12, s8
	s_and_b32 s8, s10, -8
	s_sub_i32 s11, s12, s8
	s_cmp_gt_i32 s11, -1
	s_mov_b64 s[8:9], -1
	s_cbranch_scc0 .LBB0_364
	s_lshl_b32 s12, s11, 9
	s_mov_b64 s[8:9], 0

; #define PG8_STAGE(bufoff, gbase, voff) do { _Pragma("unroll") for (int _i = 0; _i < 2; ++_i) \
;         __builtin_amdgcn_global_load_lds((const unsigned*)((const char*)(gbase) + (voff)[_i]), (PG8_LAS unsigned*)(lds + (bufoff) + ldsw + _i * 8192), 16, 0, 0); } while (0)
; #define PG8_LDA(dst, b, h) do { _Pragma("unroll") for (int m = 0; m < 4; ++m) _Pragma("unroll") for (int k = 0; k < 2; ++k) dst[m][k] = *(const PG8_LAS bf16x8*)(lds + PG8_SA(b, h) + aoff + m * 2048 + k * 1024); } while (0)
; #define PG8_LDB(dst, b, h) do { _Pragma("unroll") for (int n = 0; n < 2; ++n) _Pragma("unroll") for (int k = 0; k < 2; ++k) dst[n][k] = *(const PG8_LAS bf16x8*)(lds + PG8_SB(b, h) + boff + n * 2048 + k * 1024); } while (0)
; #define PG8_WAIT_V(n) asm volatile("s_waitcnt vmcnt(" #n ")" ::: "memory")
; #define PG8_WAIT_L(n) asm volatile("s_waitcnt lgkmcnt(" #n ")" ::: "memory")
; #define PG8_BAR __builtin_amdgcn_s_barrier()
; #define PG8_SCHED __builtin_amdgcn_sched_barrier(0)
; template <class Epi, class Sched, bool ALIGN_EPI = false, bool SP2 = false>
; __device__ __forceinline__ void gemm_phase(PG8_LAS unsigned char* lds, const Gemm g, const Sched& S, const Epi& E) {
;     ...
;         const bool has_next = S.next(ui + 1, nxt);
;         const char* nA = has_next ? (const char*)g.A + (size_t)nxt.pm * tstep : cA; const char* nB = has_next ? (const char*)g.Bt + (size_t)nxt.pn * tstep : cB;
;         for (int t = 0; t < nt; t += 2) {
;             const bool last = (t == nt - 2);
;             const char* a1 = cA + (size_t)(t + 1) * kstep;
;             const char* a2 = last ? nA : cA + (size_t)(t + 2) * kstep; const char* b2 = last ? nB : cB + (size_t)(t + 2) * kstep;
;             const char* a3 = a2 + kstep; const char* b3 = b2 + kstep;
;             if (last && has_next) S.a_ready(nxt);
;             if constexpr (SP2) {
;             PG8_LDB(B0, 0, 0); PG8_LDB(B1, 0, 1); PG8_SCHED; PG8_LDA(At, 0, 0); PG8_STAGE(PG8_SA(1, 1), a1 + hstep, voffA);
;             PG8_WAIT_V(8); PG8_WAIT_L(0); PG8_BAR; PG8_MMA(0, 0, At, B0); PG8_MMA(0, 1, At, B1); PG8_BAR; PG8_SCHED;
;             PG8_LDA(At, 0, 1); PG8_STAGE(PG8_SB(0, 0), b2, voffB); PG8_STAGE(PG8_SB(0, 1), b2 + hstep, voffB); PG8_STAGE(PG8_SA(0, 0), a2, voffA);
;             PG8_WAIT_V(8); PG8_WAIT_L(0); PG8_BAR; PG8_MMA(1, 0, At, B0); PG8_MMA(1, 1, At, B1); PG8_BAR; PG8_SCHED;
.LBB0_367:
	s_ashr_i32 s11, s10, 31
	s_lshl_b64 s[12:13], s[10:11], 19
	s_add_u32 s12, s90, s12
	s_addc_u32 s13, s91, s13
	s_and_b64 s[14:15], s[4:5], exec
	s_cselect_b32 s11, s13, s17
	s_cselect_b32 s50, s12, s16
	s_ashr_i32 s9, s8, 31
	s_lshl_b64 s[14:15], s[8:9], 19
	s_add_u32 s14, s22, s14
	s_addc_u32 s15, s23, s15
	s_and_b64 s[20:21], s[4:5], exec
	s_cselect_b32 s9, s15, s19
	s_cselect_b32 s51, s14, s18
	s_add_u32 s16, s16, 0x40080
	s_addc_u32 s17, s17, 0
	s_add_u32 s52, s18, 0x100
	s_addc_u32 s53, s19, 0
	s_mov_b32 s55, -2
	s_add_u32 s18, s16, 0xfffc0080
	s_addc_u32 s19, s17, -1
	s_add_i32 s56, 0, 0x10000
	s_cmp_eq_u32 s55, 12
	s_cselect_b32 s21, s11, s19
	s_cselect_b32 s20, s50, s18
	s_cselect_b32 s19, s9, s53
	s_cselect_b32 s18, s51, s52
	s_add_i32 s58, 0, 0x14000
	v_lshl_add_u64 v[140:141], s[16:17], 0, v[136:137]
	s_add_i32 m0, s25, 0xc000
	global_load_lds_dwordx4 v[140:141], off
	v_lshl_add_u64 v[140:141], s[16:17], 0, v[138:139]
	s_add_i32 m0, s25, 0xe000
	s_nop 0
	global_load_lds_dwordx4 v[140:141], off
	s_waitcnt vmcnt(16)
	s_waitcnt lgkmcnt(0)
	s_barrier
	s_setprio 1
	s_waitcnt lgkmcnt(0)
	v_mfma_f32_16x16x32_bf16 v[122:125], v[154:157], v[204:207], 0
	v_mfma_f32_16x16x32_bf16 v[114:117], v[162:165], v[204:207], 0
	v_mfma_f32_16x16x32_bf16 v[106:109], v[154:157], v[212:215], 0
	v_mfma_f32_16x16x32_bf16 v[98:101], v[162:165], v[212:215], 0
	v_mfma_f32_16x16x32_bf16 v[90:93], v[154:157], v[220:223], 0
	v_mfma_f32_16x16x32_bf16 v[82:85], v[162:165], v[220:223], 0
	v_mfma_f32_16x16x32_bf16 v[74:77], v[154:157], v[228:231], 0
	v_mfma_f32_16x16x32_bf16 v[66:69], v[162:165], v[228:231], 0
	v_mfma_f32_16x16x32_bf16 v[122:125], v[158:161], v[208:211], v[122:125]
	v_mfma_f32_16x16x32_bf16 v[114:117], v[166:169], v[208:211], v[114:117]
	v_mfma_f32_16x16x32_bf16 v[106:109], v[158:161], v[216:219], v[106:109]
	v_mfma_f32_16x16x32_bf16 v[98:101], v[166:169], v[216:219], v[98:101]
	v_mfma_f32_16x16x32_bf16 v[90:93], v[158:161], v[224:227], v[90:93]
	v_mfma_f32_16x16x32_bf16 v[82:85], v[166:169], v[224:227], v[82:85]
	v_mfma_f32_16x16x32_bf16 v[74:77], v[158:161], v[232:235], v[74:77]
	v_mfma_f32_16x16x32_bf16 v[66:69], v[166:169], v[232:235], v[66:69]
	s_setprio 0
	s_setprio 1
	v_mfma_f32_16x16x32_bf16 v[126:129], v[170:173], v[204:207], 0
	v_mfma_f32_16x16x32_bf16 v[118:121], v[178:181], v[204:207], 0
	v_mfma_f32_16x16x32_bf16 v[110:113], v[170:173], v[212:215], 0
	v_mfma_f32_16x16x32_bf16 v[102:105], v[178:181], v[212:215], 0
	v_mfma_f32_16x16x32_bf16 v[94:97], v[170:173], v[220:223], 0
	v_mfma_f32_16x16x32_bf16 v[86:89], v[178:181], v[220:223], 0
	v_mfma_f32_16x16x32_bf16 v[78:81], v[170:173], v[228:231], 0
	v_mfma_f32_16x16x32_bf16 v[70:73], v[178:181], v[228:231], 0
	v_mfma_f32_16x16x32_bf16 v[126:129], v[174:177], v[208:211], v[126:129]
	v_mfma_f32_16x16x32_bf16 v[118:121], v[200:203], v[208:211], v[118:121]
	v_mfma_f32_16x16x32_bf16 v[110:113], v[174:177], v[216:219], v[110:113]
	v_mfma_f32_16x16x32_bf16 v[102:105], v[200:203], v[216:219], v[102:105]
	v_mfma_f32_16x16x32_bf16 v[94:97], v[174:177], v[224:227], v[94:97]
	v_mfma_f32_16x16x32_bf16 v[86:89], v[200:203], v[224:227], v[86:89]
	v_mfma_f32_16x16x32_bf16 v[78:81], v[174:177], v[232:235], v[78:81]
	v_mfma_f32_16x16x32_bf16 v[70:73], v[200:203], v[232:235], v[70:73]
	s_setprio 0
	s_barrier
	s_add_i32 s56, s56, s24
	v_lshl_add_u64 v[140:141], s[18:19], 0, v[0:1]
	s_mov_b32 m0, s56
	ds_read_b128 v[204:207], v145 offset:16384
	ds_read_b128 v[208:211], v145 offset:17408
	ds_read_b128 v[212:215], v145 offset:18432
	ds_read_b128 v[216:219], v145 offset:19456
	ds_read_b128 v[220:223], v145 offset:20480
	ds_read_b128 v[224:227], v145 offset:21504
	ds_read_b128 v[228:231], v145 offset:22528
	ds_read_b128 v[232:235], v145 offset:23552
	global_load_lds_dwordx4 v[140:141], off
	s_add_i32 m0, s56, 0x2000
	s_add_u32 s56, s18, 0x40000
	v_lshl_add_u64 v[146:147], s[18:19], 0, v[130:131]
	s_addc_u32 s57, s19, 0
	s_add_i32 s58, s58, s24
	global_load_lds_dwordx4 v[146:147], off
	v_lshl_add_u64 v[148:149], s[56:57], 0, v[0:1]
	s_mov_b32 m0, s58
	v_lshl_add_u64 v[236:237], s[20:21], 0, v[132:133]
	global_load_lds_dwordx4 v[148:149], off
	v_lshl_add_u64 v[148:149], s[56:57], 0, v[130:131]
	s_add_i32 m0, s58, 0x2000
	s_nop 0
	global_load_lds_dwordx4 v[148:149], off
	v_lshl_add_u64 v[148:149], s[20:21], 0, v[134:135]
	s_mov_b32 m0, s25
	s_nop 0
	global_load_lds_dwordx4 v[148:149], off
	s_mov_b32 m0, s26
	s_nop 0
	global_load_lds_dwordx4 v[236:237], off
	s_waitcnt vmcnt(16)
	s_waitcnt lgkmcnt(0)
	s_barrier
	s_setprio 1
	s_waitcnt lgkmcnt(0)
	v_mfma_f32_16x16x32_bf16 v[58:61], v[154:157], v[204:207], 0
	v_mfma_f32_16x16x32_bf16 v[50:53], v[162:165], v[204:207], 0
	v_mfma_f32_16x16x32_bf16 v[42:45], v[154:157], v[212:215], 0
	v_mfma_f32_16x16x32_bf16 v[34:37], v[162:165], v[212:215], 0
	v_mfma_f32_16x16x32_bf16 v[26:29], v[154:157], v[220:223], 0
	v_mfma_f32_16x16x32_bf16 v[18:21], v[162:165], v[220:223], 0
	v_mfma_f32_16x16x32_bf16 v[10:13], v[154:157], v[228:231], 0
	v_mfma_f32_16x16x32_bf16 v[2:5], v[162:165], v[228:231], 0
	v_mfma_f32_16x16x32_bf16 v[58:61], v[158:161], v[208:211], v[58:61]
	v_mfma_f32_16x16x32_bf16 v[50:53], v[166:169], v[208:211], v[50:53]
	v_mfma_f32_16x16x32_bf16 v[42:45], v[158:161], v[216:219], v[42:45]
	v_mfma_f32_16x16x32_bf16 v[34:37], v[166:169], v[216:219], v[34:37]
	v_mfma_f32_16x16x32_bf16 v[26:29], v[158:161], v[224:227], v[26:29]
	v_mfma_f32_16x16x32_bf16 v[18:21], v[166:169], v[224:227], v[18:21]
	v_mfma_f32_16x16x32_bf16 v[10:13], v[158:161], v[232:235], v[10:13]
	v_mfma_f32_16x16x32_bf16 v[2:5], v[166:169], v[232:235], v[2:5]
	s_setprio 0
	s_setprio 1
	v_mfma_f32_16x16x32_bf16 v[62:65], v[170:173], v[204:207], 0
	v_mfma_f32_16x16x32_bf16 v[54:57], v[178:181], v[204:207], 0
	v_mfma_f32_16x16x32_bf16 v[46:49], v[170:173], v[212:215], 0
	v_mfma_f32_16x16x32_bf16 v[38:41], v[178:181], v[212:215], 0
	v_mfma_f32_16x16x32_bf16 v[30:33], v[170:173], v[220:223], 0
	v_mfma_f32_16x16x32_bf16 v[22:25], v[178:181], v[220:223], 0
	v_mfma_f32_16x16x32_bf16 v[14:17], v[170:173], v[228:231], 0
	v_mfma_f32_16x16x32_bf16 v[6:9], v[178:181], v[228:231], 0
	v_mfma_f32_16x16x32_bf16 v[62:65], v[174:177], v[208:211], v[62:65]
	v_mfma_f32_16x16x32_bf16 v[54:57], v[200:203], v[208:211], v[54:57]
	v_mfma_f32_16x16x32_bf16 v[46:49], v[174:177], v[216:219], v[46:49]
	v_mfma_f32_16x16x32_bf16 v[38:41], v[200:203], v[216:219], v[38:41]
	v_mfma_f32_16x16x32_bf16 v[30:33], v[174:177], v[224:227], v[30:33]
	v_mfma_f32_16x16x32_bf16 v[22:25], v[200:203], v[224:227], v[22:25]
	v_mfma_f32_16x16x32_bf16 v[14:17], v[174:177], v[232:235], v[14:17]
	v_mfma_f32_16x16x32_bf16 v[6:9], v[200:203], v[232:235], v[6:9]
	s_setprio 0
	s_barrier
; #define PG8_STAGE(bufoff, gbase, voff) do { _Pragma("unroll") for (int _i = 0; _i < 2; ++_i) \
;         __builtin_amdgcn_global_load_lds((const unsigned*)((const char*)(gbase) + (voff)[_i]), (PG8_LAS unsigned*)(lds + (bufoff) + ldsw + _i * 8192), 16, 0, 0); } while (0)
; #define PG8_LDA(dst, b, h) do { _Pragma("unroll") for (int m = 0; m < 4; ++m) _Pragma("unroll") for (int k = 0; k < 2; ++k) dst[m][k] = *(const PG8_LAS bf16x8*)(lds + PG8_SA(b, h) + aoff + m * 2048 + k * 1024); } while (0)
; #define PG8_LDB(dst, b, h) do { _Pragma("unroll") for (int n = 0; n < 2; ++n) _Pragma("unroll") for (int k = 0; k < 2; ++k) dst[n][k] = *(const PG8_LAS bf16x8*)(lds + PG8_SB(b, h) + boff + n * 2048 + k * 1024); } while (0)
; #define PG8_MMA(ai, bj, At, Bt) do { __builtin_amdgcn_s_setprio(1); _Pragma("unroll") for (int m = 0; m < 4; ++m) _Pragma("unroll") for (int n = 0; n < 2; ++n) _Pragma("unroll") for (int k = 0; k < 2; ++k) \
;         acc[ai][bj][m][n] = __builtin_amdgcn_mfma_f32_16x16x32_bf16(Bt[n][k], At[m][k], acc[ai][bj][m][n], 0, 0, 0); __builtin_amdgcn_s_setprio(0); } while (0)
; #define PG8_WAIT_V(n) asm volatile("s_waitcnt vmcnt(" #n ")" ::: "memory")
; #define PG8_WAIT_L(n) asm volatile("s_waitcnt lgkmcnt(" #n ")" ::: "memory")
; #define PG8_BAR __builtin_amdgcn_s_barrier()
; #define PG8_SCHED __builtin_amdgcn_sched_barrier(0)
; template <class Epi, class Sched, bool ALIGN_EPI = false, bool SP2 = false>
; __device__ __forceinline__ void gemm_phase(PG8_LAS unsigned char* lds, const Gemm g, const Sched& S, const Epi& E) {
;     ...
;             PG8_LDB(B0, 1, 0); PG8_LDB(B1, 1, 1); PG8_SCHED; PG8_LDA(At, 1, 0); PG8_STAGE(PG8_SA(0, 1), a2 + hstep, voffA);
;             PG8_WAIT_V(8); PG8_WAIT_L(0); PG8_BAR; PG8_MMA(0, 0, At, B0); PG8_MMA(0, 1, At, B1); PG8_BAR; PG8_SCHED;
	s_add_i32 s56, 0, 0x18000
	s_add_i32 s57, 0, 0x1c000
	v_add_u32_e32 v166, s56, v143
	v_add_u32_e32 v200, s57, v143
	ds_read_b128 v[154:157], v166
	ds_read_b128 v[158:161], v166 offset:1024
	ds_read_b128 v[162:165], v166 offset:2048
	ds_read_b128 v[166:169], v166 offset:3072
	ds_read_b128 v[170:173], v200
	ds_read_b128 v[174:177], v200 offset:1024
	ds_read_b128 v[178:181], v200 offset:2048
	ds_read_b128 v[200:203], v200 offset:3072
	s_add_u32 s20, s20, 0x40000
	s_addc_u32 s21, s21, 0
	s_mov_b32 m0, s27
	v_lshl_add_u64 v[238:239], s[20:21], 0, v[134:135]
	ds_read_b128 v[204:207], v145 offset:32768
	ds_read_b128 v[208:211], v145 offset:33792
	ds_read_b128 v[212:215], v145 offset:34816
	ds_read_b128 v[216:219], v145 offset:35840
	ds_read_b128 v[220:223], v145 offset:36864
	ds_read_b128 v[224:227], v145 offset:37888
	ds_read_b128 v[228:231], v145 offset:38912
	ds_read_b128 v[232:235], v145 offset:39936
	global_load_lds_dwordx4 v[238:239], off
	v_lshl_add_u64 v[238:239], s[20:21], 0, v[132:133]
	s_mov_b32 m0, s28
	s_nop 0
	global_load_lds_dwordx4 v[238:239], off
	s_waitcnt vmcnt(8)
	s_waitcnt lgkmcnt(0)
	s_barrier
	s_setprio 1
	s_waitcnt lgkmcnt(0)
	v_mfma_f32_16x16x32_bf16 v[122:125], v[154:157], v[204:207], v[122:125]
	v_mfma_f32_16x16x32_bf16 v[114:117], v[162:165], v[204:207], v[114:117]
	v_mfma_f32_16x16x32_bf16 v[106:109], v[154:157], v[212:215], v[106:109]
	v_mfma_f32_16x16x32_bf16 v[98:101], v[162:165], v[212:215], v[98:101]
	v_mfma_f32_16x16x32_bf16 v[90:93], v[154:157], v[220:223], v[90:93]
	v_mfma_f32_16x16x32_bf16 v[82:85], v[162:165], v[220:223], v[82:85]
	v_mfma_f32_16x16x32_bf16 v[74:77], v[154:157], v[228:231], v[74:77]
	v_mfma_f32_16x16x32_bf16 v[66:69], v[162:165], v[228:231], v[66:69]
	v_mfma_f32_16x16x32_bf16 v[122:125], v[158:161], v[208:211], v[122:125]
	v_mfma_f32_16x16x32_bf16 v[114:117], v[166:169], v[208:211], v[114:117]
	v_mfma_f32_16x16x32_bf16 v[106:109], v[158:161], v[216:219], v[106:109]
	v_mfma_f32_16x16x32_bf16 v[98:101], v[166:169], v[216:219], v[98:101]
	v_mfma_f32_16x16x32_bf16 v[90:93], v[158:161], v[224:227], v[90:93]
	v_mfma_f32_16x16x32_bf16 v[82:85], v[166:169], v[224:227], v[82:85]
	v_mfma_f32_16x16x32_bf16 v[74:77], v[158:161], v[232:235], v[74:77]
	v_mfma_f32_16x16x32_bf16 v[66:69], v[166:169], v[232:235], v[66:69]
	s_setprio 0
	s_setprio 1
	v_mfma_f32_16x16x32_bf16 v[126:129], v[170:173], v[204:207], v[126:129]
	v_mfma_f32_16x16x32_bf16 v[118:121], v[178:181], v[204:207], v[118:121]
	v_mfma_f32_16x16x32_bf16 v[110:113], v[170:173], v[212:215], v[110:113]
	v_mfma_f32_16x16x32_bf16 v[102:105], v[178:181], v[212:215], v[102:105]
	v_mfma_f32_16x16x32_bf16 v[94:97], v[170:173], v[220:223], v[94:97]
	v_mfma_f32_16x16x32_bf16 v[86:89], v[178:181], v[220:223], v[86:89]
	v_mfma_f32_16x16x32_bf16 v[78:81], v[170:173], v[228:231], v[78:81]
	v_mfma_f32_16x16x32_bf16 v[70:73], v[178:181], v[228:231], v[70:73]
	v_mfma_f32_16x16x32_bf16 v[126:129], v[174:177], v[208:211], v[126:129]
	v_mfma_f32_16x16x32_bf16 v[118:121], v[200:203], v[208:211], v[118:121]
	v_mfma_f32_16x16x32_bf16 v[110:113], v[174:177], v[216:219], v[110:113]
	v_mfma_f32_16x16x32_bf16 v[102:105], v[200:203], v[216:219], v[102:105]
	v_mfma_f32_16x16x32_bf16 v[94:97], v[174:177], v[224:227], v[94:97]
	v_mfma_f32_16x16x32_bf16 v[86:89], v[200:203], v[224:227], v[86:89]
	v_mfma_f32_16x16x32_bf16 v[78:81], v[174:177], v[232:235], v[78:81]
	v_mfma_f32_16x16x32_bf16 v[70:73], v[200:203], v[232:235], v[70:73]
	s_setprio 0
	s_barrier
; #define PG8_STAGE(bufoff, gbase, voff) do { _Pragma("unroll") for (int _i = 0; _i < 2; ++_i) \
;         __builtin_amdgcn_global_load_lds((const unsigned*)((const char*)(gbase) + (voff)[_i]), (PG8_LAS unsigned*)(lds + (bufoff) + ldsw + _i * 8192), 16, 0, 0); } while (0)
; #define PG8_LDA(dst, b, h) do { _Pragma("unroll") for (int m = 0; m < 4; ++m) _Pragma("unroll") for (int k = 0; k < 2; ++k) dst[m][k] = *(const PG8_LAS bf16x8*)(lds + PG8_SA(b, h) + aoff + m * 2048 + k * 1024); } while (0)
; #define PG8_MMA(ai, bj, At, Bt) do { __builtin_amdgcn_s_setprio(1); _Pragma("unroll") for (int m = 0; m < 4; ++m) _Pragma("unroll") for (int n = 0; n < 2; ++n) _Pragma("unroll") for (int k = 0; k < 2; ++k) \
;         acc[ai][bj][m][n] = __builtin_amdgcn_mfma_f32_16x16x32_bf16(Bt[n][k], At[m][k], acc[ai][bj][m][n], 0, 0, 0); __builtin_amdgcn_s_setprio(0); } while (0)
; #define PG8_WAIT_V(n) asm volatile("s_waitcnt vmcnt(" #n ")" ::: "memory")
; #define PG8_WAIT_L(n) asm volatile("s_waitcnt lgkmcnt(" #n ")" ::: "memory")
; #define PG8_BAR __builtin_amdgcn_s_barrier()
; #define PG8_SCHED __builtin_amdgcn_sched_barrier(0)
; template <class Epi, class Sched, bool ALIGN_EPI = false, bool SP2 = false>
; __device__ __forceinline__ void gemm_phase(PG8_LAS unsigned char* lds, const Gemm g, const Sched& S, const Epi& E) {
;     ...
;         for (int t = 0; t < nt; t += 2) {
;     ...
;             PG8_LDA(At, 1, 1); PG8_STAGE(PG8_SB(1, 0), b3, voffB); PG8_STAGE(PG8_SB(1, 1), b3 + hstep, voffB); PG8_STAGE(PG8_SA(1, 0), a3, voffA);
;             PG8_WAIT_V(8); PG8_WAIT_L(0); PG8_BAR; PG8_MMA(1, 0, At, B0); PG8_MMA(1, 1, At, B1); PG8_BAR; PG8_SCHED;
	s_add_i32 s20, s56, s24
	v_lshl_add_u64 v[140:141], v[140:141], 0, s[38:39]
	s_mov_b32 m0, s20
	ds_read_b128 v[204:207], v145 offset:49152
	ds_read_b128 v[208:211], v145 offset:50176
	ds_read_b128 v[212:215], v145 offset:51200
	ds_read_b128 v[216:219], v145 offset:52224
	ds_read_b128 v[220:223], v145 offset:53248
	ds_read_b128 v[224:227], v145 offset:54272
	ds_read_b128 v[228:231], v145 offset:55296
	ds_read_b128 v[232:235], v145 offset:56320
	global_load_lds_dwordx4 v[140:141], off
	s_add_i32 m0, s20, 0x2000
	s_add_u32 s18, s18, 0x40080
	v_lshl_add_u64 v[140:141], v[146:147], 0, s[38:39]
	s_addc_u32 s19, s19, 0
	s_add_i32 s20, s57, s24
	global_load_lds_dwordx4 v[140:141], off
	v_lshl_add_u64 v[140:141], s[18:19], 0, v[0:1]
	s_mov_b32 m0, s20
	s_nop 0
	global_load_lds_dwordx4 v[140:141], off
	v_lshl_add_u64 v[140:141], s[18:19], 0, v[130:131]
	s_add_i32 m0, s20, 0x2000
	s_nop 0
	global_load_lds_dwordx4 v[140:141], off
	v_lshl_add_u64 v[140:141], v[148:149], 0, s[38:39]
	s_mov_b32 m0, s29
	s_nop 0
	global_load_lds_dwordx4 v[140:141], off
	v_lshl_add_u64 v[140:141], v[236:237], 0, s[38:39]
	s_mov_b32 m0, s30
	s_nop 0
	global_load_lds_dwordx4 v[140:141], off
	s_waitcnt vmcnt(8)
	s_waitcnt lgkmcnt(0)
	s_barrier
	s_setprio 1
	s_waitcnt lgkmcnt(0)
	v_mfma_f32_16x16x32_bf16 v[58:61], v[154:157], v[204:207], v[58:61]
	v_mfma_f32_16x16x32_bf16 v[50:53], v[162:165], v[204:207], v[50:53]
	v_mfma_f32_16x16x32_bf16 v[42:45], v[154:157], v[212:215], v[42:45]
	v_mfma_f32_16x16x32_bf16 v[34:37], v[162:165], v[212:215], v[34:37]
	v_mfma_f32_16x16x32_bf16 v[26:29], v[154:157], v[220:223], v[26:29]
	v_mfma_f32_16x16x32_bf16 v[18:21], v[162:165], v[220:223], v[18:21]
	v_mfma_f32_16x16x32_bf16 v[10:13], v[154:157], v[228:231], v[10:13]
	v_mfma_f32_16x16x32_bf16 v[2:5], v[162:165], v[228:231], v[2:5]
	v_mfma_f32_16x16x32_bf16 v[58:61], v[158:161], v[208:211], v[58:61]
	v_mfma_f32_16x16x32_bf16 v[50:53], v[166:169], v[208:211], v[50:53]
	v_mfma_f32_16x16x32_bf16 v[42:45], v[158:161], v[216:219], v[42:45]
	v_mfma_f32_16x16x32_bf16 v[34:37], v[166:169], v[216:219], v[34:37]
	v_mfma_f32_16x16x32_bf16 v[26:29], v[158:161], v[224:227], v[26:29]
	v_mfma_f32_16x16x32_bf16 v[18:21], v[166:169], v[224:227], v[18:21]
	v_mfma_f32_16x16x32_bf16 v[10:13], v[158:161], v[232:235], v[10:13]
	v_mfma_f32_16x16x32_bf16 v[2:5], v[166:169], v[232:235], v[2:5]
	s_setprio 0
	s_setprio 1
	v_mfma_f32_16x16x32_bf16 v[62:65], v[170:173], v[204:207], v[62:65]
	v_mfma_f32_16x16x32_bf16 v[54:57], v[178:181], v[204:207], v[54:57]
	v_mfma_f32_16x16x32_bf16 v[46:49], v[170:173], v[212:215], v[46:49]
	v_mfma_f32_16x16x32_bf16 v[38:41], v[178:181], v[212:215], v[38:41]
	v_mfma_f32_16x16x32_bf16 v[30:33], v[170:173], v[220:223], v[30:33]
	v_mfma_f32_16x16x32_bf16 v[22:25], v[178:181], v[220:223], v[22:25]
	v_mfma_f32_16x16x32_bf16 v[14:17], v[170:173], v[228:231], v[14:17]
	v_mfma_f32_16x16x32_bf16 v[6:9], v[178:181], v[228:231], v[6:9]
	v_mfma_f32_16x16x32_bf16 v[62:65], v[174:177], v[208:211], v[62:65]
	v_mfma_f32_16x16x32_bf16 v[54:57], v[200:203], v[208:211], v[54:57]
	v_mfma_f32_16x16x32_bf16 v[46:49], v[174:177], v[216:219], v[46:49]
	v_mfma_f32_16x16x32_bf16 v[38:41], v[200:203], v[216:219], v[38:41]
	v_mfma_f32_16x16x32_bf16 v[30:33], v[174:177], v[224:227], v[30:33]
	v_mfma_f32_16x16x32_bf16 v[22:25], v[200:203], v[224:227], v[22:25]
	v_mfma_f32_16x16x32_bf16 v[14:17], v[174:177], v[232:235], v[14:17]
	v_mfma_f32_16x16x32_bf16 v[6:9], v[200:203], v[232:235], v[6:9]
	s_setprio 0
	s_barrier
	s_add_i32 s55, s55, 2
	s_add_u32 s16, s16, 0x100
	s_addc_u32 s17, s17, 0
	s_add_u32 s52, s52, 0x100
	s_addc_u32 s53, s53, 0

; #define PG8_STAGE(bufoff, gbase, voff) do { _Pragma("unroll") for (int _i = 0; _i < 2; ++_i) \
;         __builtin_amdgcn_global_load_lds((const unsigned*)((const char*)(gbase) + (voff)[_i]), (PG8_LAS unsigned*)(lds + (bufoff) + ldsw + _i * 8192), 16, 0, 0); } while (0)
; #define PG8_LDA(dst, b, h) do { _Pragma("unroll") for (int m = 0; m < 4; ++m) _Pragma("unroll") for (int k = 0; k < 2; ++k) dst[m][k] = *(const PG8_LAS bf16x8*)(lds + PG8_SA(b, h) + aoff + m * 2048 + k * 1024); } while (0)
; #define PG8_LDB(dst, b, h) do { _Pragma("unroll") for (int n = 0; n < 2; ++n) _Pragma("unroll") for (int k = 0; k < 2; ++k) dst[n][k] = *(const PG8_LAS bf16x8*)(lds + PG8_SB(b, h) + boff + n * 2048 + k * 1024); } while (0)
; #define PG8_SCHED __builtin_amdgcn_sched_barrier(0)
;     __host__ __device__ bool next(int i, Unit& u) const {
;         const long L = (long)i * G + c; if (L >= nwg) return false;
;         int wgid = (int)L; { const int q = nwg / NXCD, r = nwg % NXCD, xcd = wgid % NXCD, off = wgid / NXCD; wgid = (xcd < r ? xcd * (q + 1) : r * (q + 1) + (xcd - r) * q) + off; }
;         const int nig = WGM * nN, gid = wgid / nig, fm = gid * WGM, gsz = (nM - fm) < WGM ? (nM - fm) : WGM;
;         u.pm = fm + ((wgid % nig) % gsz); u.pn = (wgid % nig) / gsz; return true;
;     }
; template <class Epi, class Sched, bool ALIGN_EPI = false, bool SP2 = false>
; __device__ __forceinline__ void gemm_phase(PG8_LAS unsigned char* lds, const Gemm g, const Sched& S, const Epi& E) {
;     ...
;             PG8_LDB(B0, 0, 0); PG8_LDB(B1, 0, 1); PG8_SCHED; PG8_LDA(At, 0, 0); PG8_STAGE(PG8_SA(1, 1), a1 + hstep, voffA);
.LBB0_425:
	v_add_u32_e32 v142, 0x10000, v201
	v_add_u32_e32 v146, 0x14000, v201
	ds_read_b128 v[130:133], v142
	ds_read_b128 v[134:137], v142 offset:1024
	ds_read_b128 v[138:141], v142 offset:2048
	ds_read_b128 v[142:145], v142 offset:3072
	ds_read_b128 v[164:167], v146
	ds_read_b128 v[168:171], v146 offset:1024
	ds_read_b128 v[172:175], v146 offset:2048
	ds_read_b128 v[176:179], v146 offset:3072
	ds_read_b128 v[204:207], v203
	ds_read_b128 v[208:211], v203 offset:1024
	ds_read_b128 v[212:215], v203 offset:2048
	ds_read_b128 v[216:219], v203 offset:3072
	ds_read_b128 v[220:223], v203 offset:4096
	ds_read_b128 v[224:227], v203 offset:5120
	ds_read_b128 v[228:231], v203 offset:6144
	ds_read_b128 v[232:235], v203 offset:7168
	s_add_i32 s48, s48, 1
	s_mul_i32 s4, s48, s79
	s_mul_hi_u32 s5, s48, s78
	s_add_i32 s5, s5, s4
	s_mul_i32 s4, s48, s78
	s_add_u32 s12, s4, s2
	s_addc_u32 s13, s5, s3
	v_cmp_gt_i64_e32 vcc, s[12:13], v[152:153]
	v_cmp_lt_i64_e64 s[4:5], s[12:13], v[150:151]
	s_cbranch_vccnz .LBB0_431
	s_ashr_i32 s8, s12, 31
	s_lshr_b32 s8, s8, 29
	s_add_i32 s10, s12, s8
	s_and_b32 s8, s10, -8
	s_sub_i32 s11, s12, s8
	s_cmp_gt_i32 s11, -1
	s_mov_b64 s[8:9], -1
	s_cbranch_scc0 .LBB0_428
	s_lshl_b32 s12, s11, 6
	s_mov_b64 s[8:9], 0

; #define PG8_STAGE(bufoff, gbase, voff) do { _Pragma("unroll") for (int _i = 0; _i < 2; ++_i) \
;         __builtin_amdgcn_global_load_lds((const unsigned*)((const char*)(gbase) + (voff)[_i]), (PG8_LAS unsigned*)(lds + (bufoff) + ldsw + _i * 8192), 16, 0, 0); } while (0)
; #define PG8_LDA(dst, b, h) do { _Pragma("unroll") for (int m = 0; m < 4; ++m) _Pragma("unroll") for (int k = 0; k < 2; ++k) dst[m][k] = *(const PG8_LAS bf16x8*)(lds + PG8_SA(b, h) + aoff + m * 2048 + k * 1024); } while (0)
; #define PG8_LDB(dst, b, h) do { _Pragma("unroll") for (int n = 0; n < 2; ++n) _Pragma("unroll") for (int k = 0; k < 2; ++k) dst[n][k] = *(const PG8_LAS bf16x8*)(lds + PG8_SB(b, h) + boff + n * 2048 + k * 1024); } while (0)
; #define PG8_WAIT_V(n) asm volatile("s_waitcnt vmcnt(" #n ")" ::: "memory")
; #define PG8_WAIT_L(n) asm volatile("s_waitcnt lgkmcnt(" #n ")" ::: "memory")
; #define PG8_BAR __builtin_amdgcn_s_barrier()
; #define PG8_SCHED __builtin_amdgcn_sched_barrier(0)
; template <class Epi, class Sched, bool ALIGN_EPI = false, bool SP2 = false>
; __device__ __forceinline__ void gemm_phase(PG8_LAS unsigned char* lds, const Gemm g, const Sched& S, const Epi& E) {
;     ...
;         const bool has_next = S.next(ui + 1, nxt);
;         const char* nA = has_next ? (const char*)g.A + (size_t)nxt.pm * tstep : cA; const char* nB = has_next ? (const char*)g.Bt + (size_t)nxt.pn * tstep : cB;
;         for (int t = 0; t < nt; t += 2) {
;             const bool last = (t == nt - 2);
;             const char* a1 = cA + (size_t)(t + 1) * kstep;
;             const char* a2 = last ? nA : cA + (size_t)(t + 2) * kstep; const char* b2 = last ? nB : cB + (size_t)(t + 2) * kstep;
;             const char* a3 = a2 + kstep; const char* b3 = b2 + kstep;
;             if (last && has_next) S.a_ready(nxt);
;             if constexpr (SP2) {
;             PG8_LDB(B0, 0, 0); PG8_LDB(B1, 0, 1); PG8_SCHED; PG8_LDA(At, 0, 0); PG8_STAGE(PG8_SA(1, 1), a1 + hstep, voffA);
;             PG8_WAIT_V(8); PG8_WAIT_L(0); PG8_BAR; PG8_MMA(0, 0, At, B0); PG8_MMA(0, 1, At, B1); PG8_BAR; PG8_SCHED;
;             PG8_LDA(At, 0, 1); PG8_STAGE(PG8_SB(0, 0), b2, voffB); PG8_STAGE(PG8_SB(0, 1), b2 + hstep, voffB); PG8_STAGE(PG8_SA(0, 0), a2, voffA);
;             PG8_WAIT_V(8); PG8_WAIT_L(0); PG8_BAR; PG8_MMA(1, 0, At, B0); PG8_MMA(1, 1, At, B1); PG8_BAR; PG8_SCHED;
.LBB0_431:
	s_ashr_i32 s11, s10, 31
	s_lshl_b64 s[12:13], s[10:11], 21
	s_add_u32 s12, s92, s12
	s_addc_u32 s13, s93, s13
	s_and_b64 s[14:15], s[4:5], exec
	s_cselect_b32 s11, s13, s17
	s_cselect_b32 s51, s12, s16
	s_ashr_i32 s9, s8, 31
	s_lshl_b64 s[14:15], s[8:9], 21
	s_add_u32 s14, s22, s14
	s_addc_u32 s15, s23, s15
	s_and_b64 s[20:21], s[4:5], exec
	s_cselect_b32 s9, s15, s19
	s_cselect_b32 s52, s14, s18
	s_add_u32 s16, s16, 0x100080
	s_addc_u32 s17, s17, 0
	s_add_u32 s53, s18, 0x100
	s_addc_u32 s54, s19, 0
	s_mov_b32 s55, -2
	s_add_u32 s18, s16, 0xfff00080
	s_addc_u32 s19, s17, -1
	s_add_i32 s56, 0, 0x10000
	s_cmp_eq_u32 s55, 60
	s_cselect_b32 s21, s11, s19
	s_cselect_b32 s20, s51, s18
	s_cselect_b32 s19, s9, s54
	s_cselect_b32 s18, s52, s53
	s_add_i32 s58, 0, 0x14000
	v_lshl_add_u64 v[146:147], s[16:17], 0, v[160:161]
	s_add_i32 m0, s25, 0xc000
	global_load_lds_dwordx4 v[146:147], off
	v_lshl_add_u64 v[146:147], s[16:17], 0, v[162:163]
	s_add_i32 m0, s25, 0xe000
	s_nop 0
	global_load_lds_dwordx4 v[146:147], off
	s_waitcnt vmcnt(20)
	s_waitcnt lgkmcnt(0)
	s_barrier
	s_setprio 1
	s_waitcnt lgkmcnt(0)
	v_mfma_f32_16x16x32_bf16 v[126:129], v[130:133], v[204:207], 0
	v_mfma_f32_16x16x32_bf16 v[122:125], v[138:141], v[204:207], 0
	v_mfma_f32_16x16x32_bf16 v[118:121], v[130:133], v[212:215], 0
	v_mfma_f32_16x16x32_bf16 v[114:117], v[138:141], v[212:215], 0
	v_mfma_f32_16x16x32_bf16 v[110:113], v[130:133], v[220:223], 0
	v_mfma_f32_16x16x32_bf16 v[106:109], v[138:141], v[220:223], 0
	v_mfma_f32_16x16x32_bf16 v[102:105], v[130:133], v[228:231], 0
	v_mfma_f32_16x16x32_bf16 v[98:101], v[138:141], v[228:231], 0
	v_mfma_f32_16x16x32_bf16 v[126:129], v[134:137], v[208:211], v[126:129]
	v_mfma_f32_16x16x32_bf16 v[122:125], v[142:145], v[208:211], v[122:125]
	v_mfma_f32_16x16x32_bf16 v[118:121], v[134:137], v[216:219], v[118:121]
	v_mfma_f32_16x16x32_bf16 v[114:117], v[142:145], v[216:219], v[114:117]
	v_mfma_f32_16x16x32_bf16 v[110:113], v[134:137], v[224:227], v[110:113]
	v_mfma_f32_16x16x32_bf16 v[106:109], v[142:145], v[224:227], v[106:109]
	v_mfma_f32_16x16x32_bf16 v[102:105], v[134:137], v[232:235], v[102:105]
	v_mfma_f32_16x16x32_bf16 v[98:101], v[142:145], v[232:235], v[98:101]
	s_setprio 0
	s_setprio 1
	v_mfma_f32_16x16x32_bf16 v[62:65], v[164:167], v[204:207], 0
	v_mfma_f32_16x16x32_bf16 v[58:61], v[172:175], v[204:207], 0
	v_mfma_f32_16x16x32_bf16 v[54:57], v[164:167], v[212:215], 0
	v_mfma_f32_16x16x32_bf16 v[50:53], v[172:175], v[212:215], 0
	v_mfma_f32_16x16x32_bf16 v[46:49], v[164:167], v[220:223], 0
	v_mfma_f32_16x16x32_bf16 v[42:45], v[172:175], v[220:223], 0
	v_mfma_f32_16x16x32_bf16 v[38:41], v[164:167], v[228:231], 0
	v_mfma_f32_16x16x32_bf16 v[34:37], v[172:175], v[228:231], 0
	v_mfma_f32_16x16x32_bf16 v[62:65], v[168:171], v[208:211], v[62:65]
	v_mfma_f32_16x16x32_bf16 v[58:61], v[176:179], v[208:211], v[58:61]
	v_mfma_f32_16x16x32_bf16 v[54:57], v[168:171], v[216:219], v[54:57]
	v_mfma_f32_16x16x32_bf16 v[50:53], v[176:179], v[216:219], v[50:53]
	v_mfma_f32_16x16x32_bf16 v[46:49], v[168:171], v[224:227], v[46:49]
	v_mfma_f32_16x16x32_bf16 v[42:45], v[176:179], v[224:227], v[42:45]
	v_mfma_f32_16x16x32_bf16 v[38:41], v[168:171], v[232:235], v[38:41]
	v_mfma_f32_16x16x32_bf16 v[34:37], v[176:179], v[232:235], v[34:37]
	s_setprio 0
	s_barrier
	s_add_i32 s56, s56, s24
	v_lshl_add_u64 v[146:147], s[18:19], 0, v[0:1]
	s_mov_b32 m0, s56
	ds_read_b128 v[204:207], v203 offset:16384
	ds_read_b128 v[208:211], v203 offset:17408
	ds_read_b128 v[212:215], v203 offset:18432
	ds_read_b128 v[216:219], v203 offset:19456
	ds_read_b128 v[220:223], v203 offset:20480
	ds_read_b128 v[224:227], v203 offset:21504
	ds_read_b128 v[228:231], v203 offset:22528
	ds_read_b128 v[232:235], v203 offset:23552
	global_load_lds_dwordx4 v[146:147], off
	s_add_i32 m0, s56, 0x2000
	s_add_u32 s56, s18, 0x100000
	v_lshl_add_u64 v[148:149], s[18:19], 0, v[154:155]
	s_addc_u32 s57, s19, 0
	s_add_i32 s58, s58, s24
	global_load_lds_dwordx4 v[148:149], off
	v_lshl_add_u64 v[180:181], s[56:57], 0, v[0:1]
	s_mov_b32 m0, s58
	v_lshl_add_u64 v[236:237], s[20:21], 0, v[156:157]
	global_load_lds_dwordx4 v[180:181], off
	v_lshl_add_u64 v[180:181], s[56:57], 0, v[154:155]
	s_add_i32 m0, s58, 0x2000
	s_nop 0
	global_load_lds_dwordx4 v[180:181], off
	v_lshl_add_u64 v[180:181], s[20:21], 0, v[158:159]
	s_mov_b32 m0, s25
	s_nop 0
	global_load_lds_dwordx4 v[180:181], off
	s_mov_b32 m0, s26
	s_nop 0
	global_load_lds_dwordx4 v[236:237], off
	s_waitcnt vmcnt(20)
	s_waitcnt lgkmcnt(0)
	s_barrier
	s_setprio 1
	s_waitcnt lgkmcnt(0)
	v_mfma_f32_16x16x32_bf16 v[94:97], v[130:133], v[204:207], 0
	v_mfma_f32_16x16x32_bf16 v[90:93], v[138:141], v[204:207], 0
	v_mfma_f32_16x16x32_bf16 v[86:89], v[130:133], v[212:215], 0
	v_mfma_f32_16x16x32_bf16 v[82:85], v[138:141], v[212:215], 0
	v_mfma_f32_16x16x32_bf16 v[78:81], v[130:133], v[220:223], 0
	v_mfma_f32_16x16x32_bf16 v[74:77], v[138:141], v[220:223], 0
	v_mfma_f32_16x16x32_bf16 v[70:73], v[130:133], v[228:231], 0
	v_mfma_f32_16x16x32_bf16 v[66:69], v[138:141], v[228:231], 0
	v_mfma_f32_16x16x32_bf16 v[94:97], v[134:137], v[208:211], v[94:97]
	v_mfma_f32_16x16x32_bf16 v[90:93], v[142:145], v[208:211], v[90:93]
	v_mfma_f32_16x16x32_bf16 v[86:89], v[134:137], v[216:219], v[86:89]
	v_mfma_f32_16x16x32_bf16 v[82:85], v[142:145], v[216:219], v[82:85]
	v_mfma_f32_16x16x32_bf16 v[78:81], v[134:137], v[224:227], v[78:81]
	v_mfma_f32_16x16x32_bf16 v[74:77], v[142:145], v[224:227], v[74:77]
	v_mfma_f32_16x16x32_bf16 v[70:73], v[134:137], v[232:235], v[70:73]
	v_mfma_f32_16x16x32_bf16 v[66:69], v[142:145], v[232:235], v[66:69]
	s_setprio 0
	s_setprio 1
	v_mfma_f32_16x16x32_bf16 v[30:33], v[164:167], v[204:207], 0
	v_mfma_f32_16x16x32_bf16 v[26:29], v[172:175], v[204:207], 0
	v_mfma_f32_16x16x32_bf16 v[22:25], v[164:167], v[212:215], 0
	v_mfma_f32_16x16x32_bf16 v[18:21], v[172:175], v[212:215], 0
	v_mfma_f32_16x16x32_bf16 v[14:17], v[164:167], v[220:223], 0
	v_mfma_f32_16x16x32_bf16 v[10:13], v[172:175], v[220:223], 0
	v_mfma_f32_16x16x32_bf16 v[6:9], v[164:167], v[228:231], 0
	v_mfma_f32_16x16x32_bf16 v[2:5], v[172:175], v[228:231], 0
	v_mfma_f32_16x16x32_bf16 v[30:33], v[168:171], v[208:211], v[30:33]
	v_mfma_f32_16x16x32_bf16 v[26:29], v[176:179], v[208:211], v[26:29]
	v_mfma_f32_16x16x32_bf16 v[22:25], v[168:171], v[216:219], v[22:25]
	v_mfma_f32_16x16x32_bf16 v[18:21], v[176:179], v[216:219], v[18:21]
	v_mfma_f32_16x16x32_bf16 v[14:17], v[168:171], v[224:227], v[14:17]
	v_mfma_f32_16x16x32_bf16 v[10:13], v[176:179], v[224:227], v[10:13]
	v_mfma_f32_16x16x32_bf16 v[6:9], v[168:171], v[232:235], v[6:9]
	v_mfma_f32_16x16x32_bf16 v[2:5], v[176:179], v[232:235], v[2:5]
	s_setprio 0
	s_barrier
; #define PG8_STAGE(bufoff, gbase, voff) do { _Pragma("unroll") for (int _i = 0; _i < 2; ++_i) \
;         __builtin_amdgcn_global_load_lds((const unsigned*)((const char*)(gbase) + (voff)[_i]), (PG8_LAS unsigned*)(lds + (bufoff) + ldsw + _i * 8192), 16, 0, 0); } while (0)
; #define PG8_LDA(dst, b, h) do { _Pragma("unroll") for (int m = 0; m < 4; ++m) _Pragma("unroll") for (int k = 0; k < 2; ++k) dst[m][k] = *(const PG8_LAS bf16x8*)(lds + PG8_SA(b, h) + aoff + m * 2048 + k * 1024); } while (0)
; #define PG8_LDB(dst, b, h) do { _Pragma("unroll") for (int n = 0; n < 2; ++n) _Pragma("unroll") for (int k = 0; k < 2; ++k) dst[n][k] = *(const PG8_LAS bf16x8*)(lds + PG8_SB(b, h) + boff + n * 2048 + k * 1024); } while (0)
; #define PG8_MMA(ai, bj, At, Bt) do { __builtin_amdgcn_s_setprio(1); _Pragma("unroll") for (int m = 0; m < 4; ++m) _Pragma("unroll") for (int n = 0; n < 2; ++n) _Pragma("unroll") for (int k = 0; k < 2; ++k) \
;         acc[ai][bj][m][n] = __builtin_amdgcn_mfma_f32_16x16x32_bf16(Bt[n][k], At[m][k], acc[ai][bj][m][n], 0, 0, 0); __builtin_amdgcn_s_setprio(0); } while (0)
; #define PG8_WAIT_V(n) asm volatile("s_waitcnt vmcnt(" #n ")" ::: "memory")
; #define PG8_WAIT_L(n) asm volatile("s_waitcnt lgkmcnt(" #n ")" ::: "memory")
; #define PG8_BAR __builtin_amdgcn_s_barrier()
; #define PG8_SCHED __builtin_amdgcn_sched_barrier(0)
; template <class Epi, class Sched, bool ALIGN_EPI = false, bool SP2 = false>
; __device__ __forceinline__ void gemm_phase(PG8_LAS unsigned char* lds, const Gemm g, const Sched& S, const Epi& E) {
;     ...
;             PG8_LDB(B0, 1, 0); PG8_LDB(B1, 1, 1); PG8_SCHED; PG8_LDA(At, 1, 0); PG8_STAGE(PG8_SA(0, 1), a2 + hstep, voffA);
;             PG8_WAIT_V(8); PG8_WAIT_L(0); PG8_BAR; PG8_MMA(0, 0, At, B0); PG8_MMA(0, 1, At, B1); PG8_BAR; PG8_SCHED;
	s_add_i32 s56, 0, 0x18000
	s_add_i32 s57, 0, 0x1c000
	v_add_u32_e32 v142, s56, v201
	v_add_u32_e32 v176, s57, v201
	ds_read_b128 v[130:133], v142
	ds_read_b128 v[134:137], v142 offset:1024
	ds_read_b128 v[138:141], v142 offset:2048
	ds_read_b128 v[142:145], v142 offset:3072
	ds_read_b128 v[164:167], v176
	ds_read_b128 v[168:171], v176 offset:1024
	ds_read_b128 v[172:175], v176 offset:2048
	ds_read_b128 v[176:179], v176 offset:3072
	s_add_u32 s20, s20, 0x100000
	s_addc_u32 s21, s21, 0
	s_mov_b32 m0, s27
	v_lshl_add_u64 v[238:239], s[20:21], 0, v[158:159]
	ds_read_b128 v[204:207], v203 offset:32768
	ds_read_b128 v[208:211], v203 offset:33792
	ds_read_b128 v[212:215], v203 offset:34816
	ds_read_b128 v[216:219], v203 offset:35840
	ds_read_b128 v[220:223], v203 offset:36864
	ds_read_b128 v[224:227], v203 offset:37888
	ds_read_b128 v[228:231], v203 offset:38912
	ds_read_b128 v[232:235], v203 offset:39936
	global_load_lds_dwordx4 v[238:239], off
	v_lshl_add_u64 v[238:239], s[20:21], 0, v[156:157]
	s_mov_b32 m0, s28
	s_nop 0
	global_load_lds_dwordx4 v[238:239], off
	s_waitcnt vmcnt(8)
	s_waitcnt lgkmcnt(0)
	s_barrier
	s_setprio 1
	s_waitcnt lgkmcnt(0)
	v_mfma_f32_16x16x32_bf16 v[126:129], v[130:133], v[204:207], v[126:129]
	v_mfma_f32_16x16x32_bf16 v[122:125], v[138:141], v[204:207], v[122:125]
	v_mfma_f32_16x16x32_bf16 v[118:121], v[130:133], v[212:215], v[118:121]
	v_mfma_f32_16x16x32_bf16 v[114:117], v[138:141], v[212:215], v[114:117]
	v_mfma_f32_16x16x32_bf16 v[110:113], v[130:133], v[220:223], v[110:113]
	v_mfma_f32_16x16x32_bf16 v[106:109], v[138:141], v[220:223], v[106:109]
	v_mfma_f32_16x16x32_bf16 v[102:105], v[130:133], v[228:231], v[102:105]
	v_mfma_f32_16x16x32_bf16 v[98:101], v[138:141], v[228:231], v[98:101]
	v_mfma_f32_16x16x32_bf16 v[126:129], v[134:137], v[208:211], v[126:129]
	v_mfma_f32_16x16x32_bf16 v[122:125], v[142:145], v[208:211], v[122:125]
	v_mfma_f32_16x16x32_bf16 v[118:121], v[134:137], v[216:219], v[118:121]
	v_mfma_f32_16x16x32_bf16 v[114:117], v[142:145], v[216:219], v[114:117]
	v_mfma_f32_16x16x32_bf16 v[110:113], v[134:137], v[224:227], v[110:113]
	v_mfma_f32_16x16x32_bf16 v[106:109], v[142:145], v[224:227], v[106:109]
	v_mfma_f32_16x16x32_bf16 v[102:105], v[134:137], v[232:235], v[102:105]
	v_mfma_f32_16x16x32_bf16 v[98:101], v[142:145], v[232:235], v[98:101]
	s_setprio 0
	s_setprio 1
	v_mfma_f32_16x16x32_bf16 v[62:65], v[164:167], v[204:207], v[62:65]
	v_mfma_f32_16x16x32_bf16 v[58:61], v[172:175], v[204:207], v[58:61]
	v_mfma_f32_16x16x32_bf16 v[54:57], v[164:167], v[212:215], v[54:57]
	v_mfma_f32_16x16x32_bf16 v[50:53], v[172:175], v[212:215], v[50:53]
	v_mfma_f32_16x16x32_bf16 v[46:49], v[164:167], v[220:223], v[46:49]
	v_mfma_f32_16x16x32_bf16 v[42:45], v[172:175], v[220:223], v[42:45]
	v_mfma_f32_16x16x32_bf16 v[38:41], v[164:167], v[228:231], v[38:41]
	v_mfma_f32_16x16x32_bf16 v[34:37], v[172:175], v[228:231], v[34:37]
	v_mfma_f32_16x16x32_bf16 v[62:65], v[168:171], v[208:211], v[62:65]
	v_mfma_f32_16x16x32_bf16 v[58:61], v[176:179], v[208:211], v[58:61]
	v_mfma_f32_16x16x32_bf16 v[54:57], v[168:171], v[216:219], v[54:57]
	v_mfma_f32_16x16x32_bf16 v[50:53], v[176:179], v[216:219], v[50:53]
	v_mfma_f32_16x16x32_bf16 v[46:49], v[168:171], v[224:227], v[46:49]
	v_mfma_f32_16x16x32_bf16 v[42:45], v[176:179], v[224:227], v[42:45]
	v_mfma_f32_16x16x32_bf16 v[38:41], v[168:171], v[232:235], v[38:41]
	v_mfma_f32_16x16x32_bf16 v[34:37], v[176:179], v[232:235], v[34:37]
	s_setprio 0
	s_barrier
; #define PG8_STAGE(bufoff, gbase, voff) do { _Pragma("unroll") for (int _i = 0; _i < 2; ++_i) \
;         __builtin_amdgcn_global_load_lds((const unsigned*)((const char*)(gbase) + (voff)[_i]), (PG8_LAS unsigned*)(lds + (bufoff) + ldsw + _i * 8192), 16, 0, 0); } while (0)
; #define PG8_LDA(dst, b, h) do { _Pragma("unroll") for (int m = 0; m < 4; ++m) _Pragma("unroll") for (int k = 0; k < 2; ++k) dst[m][k] = *(const PG8_LAS bf16x8*)(lds + PG8_SA(b, h) + aoff + m * 2048 + k * 1024); } while (0)
; #define PG8_MMA(ai, bj, At, Bt) do { __builtin_amdgcn_s_setprio(1); _Pragma("unroll") for (int m = 0; m < 4; ++m) _Pragma("unroll") for (int n = 0; n < 2; ++n) _Pragma("unroll") for (int k = 0; k < 2; ++k) \
;         acc[ai][bj][m][n] = __builtin_amdgcn_mfma_f32_16x16x32_bf16(Bt[n][k], At[m][k], acc[ai][bj][m][n], 0, 0, 0); __builtin_amdgcn_s_setprio(0); } while (0)
; #define PG8_WAIT_V(n) asm volatile("s_waitcnt vmcnt(" #n ")" ::: "memory")
; #define PG8_WAIT_L(n) asm volatile("s_waitcnt lgkmcnt(" #n ")" ::: "memory")
; #define PG8_BAR __builtin_amdgcn_s_barrier()
; #define PG8_SCHED __builtin_amdgcn_sched_barrier(0)
; template <class Epi, class Sched, bool ALIGN_EPI = false, bool SP2 = false>
; __device__ __forceinline__ void gemm_phase(PG8_LAS unsigned char* lds, const Gemm g, const Sched& S, const Epi& E) {
;     ...
;         for (int t = 0; t < nt; t += 2) {
;     ...
;             PG8_LDA(At, 1, 1); PG8_STAGE(PG8_SB(1, 0), b3, voffB); PG8_STAGE(PG8_SB(1, 1), b3 + hstep, voffB); PG8_STAGE(PG8_SA(1, 0), a3, voffA);
;             PG8_WAIT_V(8); PG8_WAIT_L(0); PG8_BAR; PG8_MMA(1, 0, At, B0); PG8_MMA(1, 1, At, B1); PG8_BAR; PG8_SCHED;
	s_add_i32 s20, s56, s24
	v_lshl_add_u64 v[146:147], v[146:147], 0, s[38:39]
	s_mov_b32 m0, s20
	ds_read_b128 v[204:207], v203 offset:49152
	ds_read_b128 v[208:211], v203 offset:50176
	ds_read_b128 v[212:215], v203 offset:51200
	ds_read_b128 v[216:219], v203 offset:52224
	ds_read_b128 v[220:223], v203 offset:53248
	ds_read_b128 v[224:227], v203 offset:54272
	ds_read_b128 v[228:231], v203 offset:55296
	ds_read_b128 v[232:235], v203 offset:56320
	global_load_lds_dwordx4 v[146:147], off
	s_add_i32 m0, s20, 0x2000
	s_add_u32 s18, s18, 0x100080
	v_lshl_add_u64 v[146:147], v[148:149], 0, s[38:39]
	s_addc_u32 s19, s19, 0
	s_add_i32 s20, s57, s24
	global_load_lds_dwordx4 v[146:147], off
	v_lshl_add_u64 v[146:147], s[18:19], 0, v[0:1]
	s_mov_b32 m0, s20
	s_nop 0
	global_load_lds_dwordx4 v[146:147], off
	v_lshl_add_u64 v[146:147], s[18:19], 0, v[154:155]
	s_add_i32 m0, s20, 0x2000
	s_nop 0
	global_load_lds_dwordx4 v[146:147], off
	v_lshl_add_u64 v[146:147], v[180:181], 0, s[38:39]
	s_mov_b32 m0, s31
	s_nop 0
	global_load_lds_dwordx4 v[146:147], off
	v_lshl_add_u64 v[146:147], v[236:237], 0, s[38:39]
	s_mov_b32 m0, s33
	s_nop 0
	global_load_lds_dwordx4 v[146:147], off
	s_waitcnt vmcnt(8)
	s_waitcnt lgkmcnt(0)
	s_barrier
	s_setprio 1
	s_waitcnt lgkmcnt(0)
	v_mfma_f32_16x16x32_bf16 v[94:97], v[130:133], v[204:207], v[94:97]
	v_mfma_f32_16x16x32_bf16 v[90:93], v[138:141], v[204:207], v[90:93]
	v_mfma_f32_16x16x32_bf16 v[86:89], v[130:133], v[212:215], v[86:89]
	v_mfma_f32_16x16x32_bf16 v[82:85], v[138:141], v[212:215], v[82:85]
	v_mfma_f32_16x16x32_bf16 v[78:81], v[130:133], v[220:223], v[78:81]
	v_mfma_f32_16x16x32_bf16 v[74:77], v[138:141], v[220:223], v[74:77]
	v_mfma_f32_16x16x32_bf16 v[70:73], v[130:133], v[228:231], v[70:73]
	v_mfma_f32_16x16x32_bf16 v[66:69], v[138:141], v[228:231], v[66:69]
	v_mfma_f32_16x16x32_bf16 v[94:97], v[134:137], v[208:211], v[94:97]
	v_mfma_f32_16x16x32_bf16 v[90:93], v[142:145], v[208:211], v[90:93]
	v_mfma_f32_16x16x32_bf16 v[86:89], v[134:137], v[216:219], v[86:89]
	v_mfma_f32_16x16x32_bf16 v[82:85], v[142:145], v[216:219], v[82:85]
	v_mfma_f32_16x16x32_bf16 v[78:81], v[134:137], v[224:227], v[78:81]
	v_mfma_f32_16x16x32_bf16 v[74:77], v[142:145], v[224:227], v[74:77]
	v_mfma_f32_16x16x32_bf16 v[70:73], v[134:137], v[232:235], v[70:73]
	v_mfma_f32_16x16x32_bf16 v[66:69], v[142:145], v[232:235], v[66:69]
	s_setprio 0
	s_setprio 1
	v_mfma_f32_16x16x32_bf16 v[30:33], v[164:167], v[204:207], v[30:33]
	v_mfma_f32_16x16x32_bf16 v[26:29], v[172:175], v[204:207], v[26:29]
	v_mfma_f32_16x16x32_bf16 v[22:25], v[164:167], v[212:215], v[22:25]
	v_mfma_f32_16x16x32_bf16 v[18:21], v[172:175], v[212:215], v[18:21]
	v_mfma_f32_16x16x32_bf16 v[14:17], v[164:167], v[220:223], v[14:17]
	v_mfma_f32_16x16x32_bf16 v[10:13], v[172:175], v[220:223], v[10:13]
	v_mfma_f32_16x16x32_bf16 v[6:9], v[164:167], v[228:231], v[6:9]
	v_mfma_f32_16x16x32_bf16 v[2:5], v[172:175], v[228:231], v[2:5]
	v_mfma_f32_16x16x32_bf16 v[30:33], v[168:171], v[208:211], v[30:33]
	v_mfma_f32_16x16x32_bf16 v[26:29], v[176:179], v[208:211], v[26:29]
	v_mfma_f32_16x16x32_bf16 v[22:25], v[168:171], v[216:219], v[22:25]
	v_mfma_f32_16x16x32_bf16 v[18:21], v[176:179], v[216:219], v[18:21]
	v_mfma_f32_16x16x32_bf16 v[14:17], v[168:171], v[224:227], v[14:17]
	v_mfma_f32_16x16x32_bf16 v[10:13], v[176:179], v[224:227], v[10:13]
	v_mfma_f32_16x16x32_bf16 v[6:9], v[168:171], v[232:235], v[6:9]
	v_mfma_f32_16x16x32_bf16 v[2:5], v[176:179], v[232:235], v[2:5]
	s_setprio 0
	s_barrier
	s_add_i32 s55, s55, 2
	s_add_u32 s16, s16, 0x100
	s_addc_u32 s17, s17, 0
	s_add_u32 s53, s53, 0x100
	s_addc_u32 s54, s54, 0

; #define PG8_STAGE(bufoff, gbase, voff) do { _Pragma("unroll") for (int _i = 0; _i < 2; ++_i) \
;         __builtin_amdgcn_global_load_lds((const unsigned*)((const char*)(gbase) + (voff)[_i]), (PG8_LAS unsigned*)(lds + (bufoff) + ldsw + _i * 8192), 16, 0, 0); } while (0)
; #define PG8_WAIT_V(n) asm volatile("s_waitcnt vmcnt(" #n ")" ::: "memory")
; #define PG8_BAR __builtin_amdgcn_s_barrier()
; template <class Epi, class Sched, bool ALIGN_EPI = false, bool SP2 = false>
; __device__ __forceinline__ void gemm_phase(PG8_LAS unsigned char* lds, const Gemm g, const Sched& S, const Epi& E) {
;     ...
;     for (int i = 0; i < 2; ++i) { int R, C; stage_rc(tid * 16 + i * 8192, R, C); const int Rb = Epi::PERM ? ((R & ~31) + perm32(R & 31)) : R;
;         voffA[i] = (unsigned)(R * K + C) * 2u; voffB[i] = (unsigned)(Rb * K + C) * 2u; }
;     const size_t kstep = (size_t)(BK * 2);
;     const size_t hstep = (size_t)HALF * K * 2;
;     const size_t tstep = 2 * hstep;
;     const unsigned ldsw = (unsigned)wid * 1024u;
;     const int aoff = lds_byte(wr * 64 + fr, fq * 8), boff = lds_byte(wc * 32 + fr, fq * 8);
;     ...
;     if constexpr (SP2) {
;         PG8_STAGE(PG8_SB(0, 0), cB, voffB); PG8_STAGE(PG8_SB(0, 1), cB + hstep, voffB); PG8_STAGE(PG8_SA(0, 0), cA, voffA); PG8_STAGE(PG8_SA(0, 1), cA + hstep, voffA);
;         if (wr == 1) PG8_BAR;
;         PG8_WAIT_V(2); PG8_BAR;
;         PG8_STAGE(PG8_SB(1, 0), cB + kstep, voffB); PG8_STAGE(PG8_SA(1, 0), cA + kstep, voffA); PG8_STAGE(PG8_SB(1, 1), cB + hstep + kstep, voffB);
;         PG8_WAIT_V(6); PG8_BAR;
.LBB0_552:
	s_and_b64 s[8:9], s[44:45], exec
	s_movk_i32 s8, 0xc00
	s_cselect_b32 s44, s8, 0x1000
	s_cselect_b32 s45, 12, 16
	s_cselect_b32 s54, 0, 8
	s_and_b32 s7, s7, 3
	s_add_i32 m0, s50, 0x18000
	v_lshl_add_u64 v[8:9], v[8:9], 0, s[38:39]
	s_lshl_b32 s10, s6, 13
	s_lshl_b32 s11, s7, 12
	s_waitcnt vmcnt(2)
	s_barrier
	global_load_lds_dwordx4 v[8:9], off
	v_lshl_add_u64 v[6:7], v[6:7], 0, s[38:39]
	s_add_i32 m0, s50, 0x1a000
	s_add_i32 s55, s50, 0x8000
	s_add_i32 s56, s50, 0xa000
	global_load_lds_dwordx4 v[6:7], off
	v_lshl_add_u64 v[2:3], v[2:3], 0, s[38:39]
	s_mov_b32 m0, s55
	s_add_u32 s8, s24, 0x40080
	global_load_lds_dwordx4 v[2:3], off
	v_lshl_add_u64 v[2:3], v[4:5], 0, s[38:39]
	s_mov_b32 m0, s56
	s_addc_u32 s9, s25, 0
	global_load_lds_dwordx4 v[2:3], off
	s_add_i32 m0, s50, 0x1c000
	v_lshl_add_u64 v[2:3], s[8:9], 0, v[158:159]
	global_load_lds_dwordx4 v[2:3], off
	v_lshl_add_u64 v[2:3], s[8:9], 0, v[154:155]
	s_add_i32 m0, s50, 0x1e000
	v_bfe_u32 v4, v0, 4, 2
	global_load_lds_dwordx4 v[2:3], off
	v_and_b32_e32 v3, 15, v0
	v_lshlrev_b32_e32 v5, 4, v4
	v_lshlrev_b32_e32 v0, 2, v0
	v_lshl_or_b32 v174, s6, 6, v3
	v_lshl_or_b32 v3, v3, 6, v5
	v_and_b32_e32 v0, 32, v0
	v_bitop3_b32 v5, v3, s10, v0 bitop3:0xde
	v_bitop3_b32 v175, v3, s11, v0 bitop3:0xde
	v_lshlrev_b32_e32 v3, 14, v14
	v_and_b32_e32 v3, 0xffff8000, v3
	s_sext_i32_i16 s59, s4
	v_lshlrev_b32_e32 v2, 3, v4
	s_cmpk_lt_u32 s5, 0x100
	v_cmp_lt_u32_e64 s[4:5], 1, v4
	v_lshlrev_b32_e32 v0, 5, v4
	v_lshl_add_u32 v3, v13, 11, v3
	v_and_b32_e32 v4, 1, v14
	v_lshl_or_b32 v3, v4, 6, v3
	v_lshl_add_u32 v164, v15, 1, v3
	v_lshlrev_b32_e32 v3, 14, v10
	v_readlane_b32 s12, v253, 40
	v_and_b32_e32 v3, 0xffff8000, v3
	s_waitcnt vmcnt(6)
	v_readlane_b32 s13, v253, 41
	v_lshl_add_u32 v3, v11, 11, v3
	v_and_b32_e32 v4, 1, v10
	s_cselect_b64 s[8:9], -1, 0
	s_cmp_lg_u32 s7, 0
	v_lshl_add_u64 v[162:163], s[12:13], 0, v[0:1]
	v_lshl_or_b32 v0, s7, 5, v2
	v_lshl_or_b32 v3, v4, 6, v3
	s_mov_b32 s57, 0
	s_cselect_b64 s[10:11], -1, 0
	s_lshr_b32 s58, s54, 1
	v_lshl_or_b32 v176, s7, 6, v2
	v_mov_b32_e32 v165, v1
	v_lshl_add_u32 v166, v12, 1, v3
	v_mov_b32_e32 v167, v1
	v_add_u32_e32 v177, 0, v5
	v_lshlrev_b32_e32 v178, 1, v0
	v_lshlrev_b32_e32 v179, 2, v2
	s_barrier
	s_waitcnt vmcnt(0)
	s_branch .LBB0_555

; #define PG8_STAGE(bufoff, gbase, voff) do { _Pragma("unroll") for (int _i = 0; _i < 2; ++_i) \
;         __builtin_amdgcn_global_load_lds((const unsigned*)((const char*)(gbase) + (voff)[_i]), (PG8_LAS unsigned*)(lds + (bufoff) + ldsw + _i * 8192), 16, 0, 0); } while (0)
; #define PG8_LDA(dst, b, h) do { _Pragma("unroll") for (int m = 0; m < 4; ++m) _Pragma("unroll") for (int k = 0; k < 2; ++k) dst[m][k] = *(const PG8_LAS bf16x8*)(lds + PG8_SA(b, h) + aoff + m * 2048 + k * 1024); } while (0)
; #define PG8_LDB(dst, b, h) do { _Pragma("unroll") for (int n = 0; n < 2; ++n) _Pragma("unroll") for (int k = 0; k < 2; ++k) dst[n][k] = *(const PG8_LAS bf16x8*)(lds + PG8_SB(b, h) + boff + n * 2048 + k * 1024); } while (0)
; #define PG8_BAR __builtin_amdgcn_s_barrier()
;     __host__ __device__ bool next(int i, Unit& u) const {
;         const long L = (long)i * G + c; if (L >= nwg) return false;
;         int wgid = (int)L; { const int q = nwg / NXCD, r = nwg % NXCD, xcd = wgid % NXCD, off = wgid / NXCD; wgid = (xcd < r ? xcd * (q + 1) : r * (q + 1) + (xcd - r) * q) + off; }
;         const int nig = WGM * nN, gid = wgid / nig, fm = gid * WGM, gsz = (nM - fm) < WGM ? (nM - fm) : WGM;
;         u.pm = fm + ((wgid % nig) % gsz); u.pn = (wgid % nig) / gsz; return true;
;     }
; template <class Epi, class Sched, bool ALIGN_EPI = false, bool SP2 = false>
; __device__ __forceinline__ void gemm_phase(PG8_LAS unsigned char* lds, const Gemm g, const Sched& S, const Epi& E) {
;     ...
;         const bool has_next = S.next(ui + 1, nxt);
;         const char* nA = has_next ? (const char*)g.A + (size_t)nxt.pm * tstep : cA; const char* nB = has_next ? (const char*)g.Bt + (size_t)nxt.pn * tstep : cB;
;         for (int t = 0; t < nt; t += 2) {
;             const bool last = (t == nt - 2);
;             const char* a1 = cA + (size_t)(t + 1) * kstep;
;             const char* a2 = last ? nA : cA + (size_t)(t + 2) * kstep; const char* b2 = last ? nB : cB + (size_t)(t + 2) * kstep;
;             const char* a3 = a2 + kstep; const char* b3 = b2 + kstep;
;             if (last && has_next) S.a_ready(nxt);
;             if constexpr (SP2) {
;             PG8_LDB(B0, 0, 0); PG8_LDB(B1, 0, 1); PG8_SCHED; PG8_LDA(At, 0, 0); PG8_STAGE(PG8_SA(1, 1), a1 + hstep, voffA);
;             PG8_WAIT_V(8); PG8_WAIT_L(0); PG8_BAR; PG8_MMA(0, 0, At, B0); PG8_MMA(0, 1, At, B1); PG8_BAR; PG8_SCHED;
.LBB0_555:
	v_add_u32_e32 v0, 0x10000, v175
	ds_read_b128 v[130:133], v0
	ds_read_b128 v[134:137], v0 offset:1024
	ds_read_b128 v[138:141], v0 offset:2048
	ds_read_b128 v[142:145], v0 offset:3072
	v_add_u32_e32 v0, 0x14000, v175
	ds_read_b128 v[168:171], v0
	ds_read_b128 v[200:203], v0 offset:1024
	ds_read_b128 v[204:207], v0 offset:2048
	ds_read_b128 v[208:211], v0 offset:3072
	ds_read_b128 v[212:215], v177
	ds_read_b128 v[216:219], v177 offset:1024
	ds_read_b128 v[220:223], v177 offset:2048
	ds_read_b128 v[224:227], v177 offset:3072
	ds_read_b128 v[228:231], v177 offset:4096
	ds_read_b128 v[232:235], v177 offset:5120
	ds_read_b128 v[236:239], v177 offset:6144
	ds_read_b128 v[240:243], v177 offset:7168
	s_add_i32 s57, s57, 1
	s_mul_i32 s6, s57, s79
	s_mul_hi_u32 s7, s57, s78
	s_add_i32 s7, s7, s6
	s_mul_i32 s6, s57, s78
	s_add_u32 s16, s6, s2
	s_addc_u32 s17, s7, s3
	v_mov_b64_e32 v[2:3], s[86:87]
	v_cmp_ge_i64_e32 vcc, s[16:17], v[2:3]
	v_cmp_lt_i64_e64 s[6:7], s[16:17], v[2:3]
	s_cbranch_vccnz .LBB0_557
	s_ashr_i32 s12, s16, 31
	s_lshr_b32 s12, s12, 29
	s_add_i32 s12, s16, s12
	s_ashr_i32 s13, s12, 3
	s_and_b32 s12, s12, -8
	s_sub_i32 s12, s16, s12
	s_cmp_lt_i32 s12, 0
	s_cselect_b32 s14, s33, s31
	s_mul_i32 s12, s14, s12
	s_add_i32 s12, s12, s13
	s_abs_i32 s14, s12
	s_mul_hi_u32 s15, s14, s49
	s_mul_i32 s16, s15, s47
	s_ashr_i32 s13, s12, 31
	s_sub_i32 s14, s14, s16
	s_xor_b32 s13, s13, s48
	s_add_i32 s16, s15, 1
	s_sub_i32 s17, s14, s47
	s_cmp_ge_u32 s14, s47
	s_cselect_b32 s15, s16, s15
	s_cselect_b32 s14, s17, s14
	s_add_i32 s16, s15, 1
	s_cmp_ge_u32 s14, s47
	s_cselect_b32 s14, s16, s15
	s_xor_b32 s14, s14, s13
	s_sub_i32 s13, s14, s13
	s_lshl_b32 s14, s13, 3
	s_sub_i32 s15, 0x80, s14
	s_min_i32 s15, s15, 8
	s_abs_i32 s16, s15
	v_cvt_f32_u32_e32 v0, s16
	s_sub_i32 s18, 0, s16
	s_mul_i32 s13, s13, s46
	s_sub_i32 s13, s12, s13
	v_rcp_iflag_f32_e32 v0, v0
	s_abs_i32 s17, s13
	s_xor_b32 s12, s13, s15
	s_ashr_i32 s12, s12, 31
	v_mul_f32_e32 v0, 0x4f7ffffe, v0
	v_cvt_u32_f32_e32 v0, v0
	s_nop 0
	v_readfirstlane_b32 s19, v0
	s_mul_i32 s18, s18, s19
	s_mul_hi_u32 s18, s19, s18
	s_add_i32 s19, s19, s18
	s_mul_hi_u32 s18, s17, s19
	s_mul_i32 s19, s18, s16
	s_sub_i32 s17, s17, s19
	s_add_i32 s19, s18, 1
	s_sub_i32 s21, s17, s16
	s_cmp_ge_u32 s17, s16
	s_cselect_b32 s18, s19, s18
	s_cselect_b32 s17, s21, s17
	s_add_i32 s19, s18, 1
	s_cmp_ge_u32 s17, s16
	s_cselect_b32 s16, s19, s18
	s_xor_b32 s16, s16, s12
	s_sub_i32 s12, s16, s12
	s_mul_i32 s15, s12, s15
	s_sub_i32 s13, s13, s15
	s_add_i32 s14, s13, s14
.LBB0_557:
	s_ashr_i32 s15, s14, 31
	s_lshl_b64 s[16:17], s[14:15], 19
	s_add_u32 s16, s90, s16
	s_addc_u32 s17, s91, s17
	s_and_b64 s[18:19], s[6:7], exec
	s_cselect_b32 s15, s17, s23
	s_cselect_b32 s21, s16, s22
	s_ashr_i32 s13, s12, 31
	s_lshl_b64 s[18:19], s[12:13], 19
	s_add_u32 s18, s28, s18
	s_addc_u32 s19, s29, s19
	s_and_b64 s[26:27], s[6:7], exec
	s_cselect_b32 s13, s19, s25
	s_cselect_b32 s60, s18, s24
	s_add_u32 s22, s22, 0x40080
	s_addc_u32 s23, s23, 0
	s_add_u32 s61, s24, 0x100
	s_addc_u32 s62, s25, 0
	s_mov_b32 s63, -2
	s_add_u32 s24, s22, 0xfffc0080
	s_addc_u32 s25, s23, -1
	s_add_i32 s64, 0, 0x10000
	s_cmp_eq_u32 s63, 12
	s_cselect_b32 s27, s15, s25
	s_cselect_b32 s26, s21, s24
	s_cselect_b32 s25, s13, s62
	s_cselect_b32 s24, s60, s61
	s_add_i32 s66, 0, 0x14000
	v_lshl_add_u64 v[146:147], s[22:23], 0, v[164:165]
	s_add_i32 m0, s50, 0xc000
	global_load_lds_dwordx4 v[146:147], off
	v_lshl_add_u64 v[146:147], s[22:23], 0, v[166:167]
	s_add_i32 m0, s50, 0xe000
	s_nop 0
	global_load_lds_dwordx4 v[146:147], off
	s_waitcnt vmcnt(24)
	s_waitcnt lgkmcnt(0)
	s_barrier
	s_setprio 1
	s_waitcnt lgkmcnt(0)
	v_mfma_f32_16x16x32_bf16 v[126:129], v[130:133], v[212:215], 0
	v_mfma_f32_16x16x32_bf16 v[122:125], v[138:141], v[212:215], 0
	v_mfma_f32_16x16x32_bf16 v[114:117], v[130:133], v[220:223], 0
	v_mfma_f32_16x16x32_bf16 v[106:109], v[138:141], v[220:223], 0
	v_mfma_f32_16x16x32_bf16 v[94:97], v[130:133], v[228:231], 0
	v_mfma_f32_16x16x32_bf16 v[90:93], v[138:141], v[228:231], 0
	v_mfma_f32_16x16x32_bf16 v[82:85], v[130:133], v[236:239], 0
	v_mfma_f32_16x16x32_bf16 v[74:77], v[138:141], v[236:239], 0
	v_mfma_f32_16x16x32_bf16 v[126:129], v[134:137], v[216:219], v[126:129]
	v_mfma_f32_16x16x32_bf16 v[122:125], v[142:145], v[216:219], v[122:125]
	v_mfma_f32_16x16x32_bf16 v[114:117], v[134:137], v[224:227], v[114:117]
	v_mfma_f32_16x16x32_bf16 v[106:109], v[142:145], v[224:227], v[106:109]
	v_mfma_f32_16x16x32_bf16 v[94:97], v[134:137], v[232:235], v[94:97]
	v_mfma_f32_16x16x32_bf16 v[90:93], v[142:145], v[232:235], v[90:93]
	v_mfma_f32_16x16x32_bf16 v[82:85], v[134:137], v[240:243], v[82:85]
	v_mfma_f32_16x16x32_bf16 v[74:77], v[142:145], v[240:243], v[74:77]
	s_setprio 0
	s_setprio 1
	v_mfma_f32_16x16x32_bf16 v[118:121], v[168:171], v[212:215], 0
	v_mfma_f32_16x16x32_bf16 v[110:113], v[204:207], v[212:215], 0
	v_mfma_f32_16x16x32_bf16 v[102:105], v[168:171], v[220:223], 0
	v_mfma_f32_16x16x32_bf16 v[98:101], v[204:207], v[220:223], 0
	v_mfma_f32_16x16x32_bf16 v[86:89], v[168:171], v[228:231], 0
	v_mfma_f32_16x16x32_bf16 v[78:81], v[204:207], v[228:231], 0
	v_mfma_f32_16x16x32_bf16 v[70:73], v[168:171], v[236:239], 0
	v_mfma_f32_16x16x32_bf16 v[66:69], v[204:207], v[236:239], 0
	v_mfma_f32_16x16x32_bf16 v[118:121], v[200:203], v[216:219], v[118:121]
	v_mfma_f32_16x16x32_bf16 v[110:113], v[208:211], v[216:219], v[110:113]
	v_mfma_f32_16x16x32_bf16 v[102:105], v[200:203], v[224:227], v[102:105]
	v_mfma_f32_16x16x32_bf16 v[98:101], v[208:211], v[224:227], v[98:101]
	v_mfma_f32_16x16x32_bf16 v[86:89], v[200:203], v[232:235], v[86:89]
	v_mfma_f32_16x16x32_bf16 v[78:81], v[208:211], v[232:235], v[78:81]
	v_mfma_f32_16x16x32_bf16 v[70:73], v[200:203], v[240:243], v[70:73]
	v_mfma_f32_16x16x32_bf16 v[66:69], v[208:211], v[240:243], v[66:69]
	s_setprio 0
	s_barrier
; #define PG8_STAGE(bufoff, gbase, voff) do { _Pragma("unroll") for (int _i = 0; _i < 2; ++_i) \
;         __builtin_amdgcn_global_load_lds((const unsigned*)((const char*)(gbase) + (voff)[_i]), (PG8_LAS unsigned*)(lds + (bufoff) + ldsw + _i * 8192), 16, 0, 0); } while (0)
; #define PG8_LDA(dst, b, h) do { _Pragma("unroll") for (int m = 0; m < 4; ++m) _Pragma("unroll") for (int k = 0; k < 2; ++k) dst[m][k] = *(const PG8_LAS bf16x8*)(lds + PG8_SA(b, h) + aoff + m * 2048 + k * 1024); } while (0)
; #define PG8_LDB(dst, b, h) do { _Pragma("unroll") for (int n = 0; n < 2; ++n) _Pragma("unroll") for (int k = 0; k < 2; ++k) dst[n][k] = *(const PG8_LAS bf16x8*)(lds + PG8_SB(b, h) + boff + n * 2048 + k * 1024); } while (0)
; #define PG8_MMA(ai, bj, At, Bt) do { __builtin_amdgcn_s_setprio(1); _Pragma("unroll") for (int m = 0; m < 4; ++m) _Pragma("unroll") for (int n = 0; n < 2; ++n) _Pragma("unroll") for (int k = 0; k < 2; ++k) \
;         acc[ai][bj][m][n] = __builtin_amdgcn_mfma_f32_16x16x32_bf16(Bt[n][k], At[m][k], acc[ai][bj][m][n], 0, 0, 0); __builtin_amdgcn_s_setprio(0); } while (0)
; #define PG8_WAIT_V(n) asm volatile("s_waitcnt vmcnt(" #n ")" ::: "memory")
; #define PG8_WAIT_L(n) asm volatile("s_waitcnt lgkmcnt(" #n ")" ::: "memory")
; #define PG8_BAR __builtin_amdgcn_s_barrier()
; #define PG8_SCHED __builtin_amdgcn_sched_barrier(0)
; template <class Epi, class Sched, bool ALIGN_EPI = false, bool SP2 = false>
; __device__ __forceinline__ void gemm_phase(PG8_LAS unsigned char* lds, const Gemm g, const Sched& S, const Epi& E) {
;     ...
;             PG8_LDA(At, 0, 1); PG8_STAGE(PG8_SB(0, 0), b2, voffB); PG8_STAGE(PG8_SB(0, 1), b2 + hstep, voffB); PG8_STAGE(PG8_SA(0, 0), a2, voffA);
;             PG8_WAIT_V(8); PG8_WAIT_L(0); PG8_BAR; PG8_MMA(1, 0, At, B0); PG8_MMA(1, 1, At, B1); PG8_BAR; PG8_SCHED;
;             PG8_LDB(B0, 1, 0); PG8_LDB(B1, 1, 1); PG8_SCHED; PG8_LDA(At, 1, 0); PG8_STAGE(PG8_SA(0, 1), a2 + hstep, voffA);
;             PG8_WAIT_V(8); PG8_WAIT_L(0); PG8_BAR; PG8_MMA(0, 0, At, B0); PG8_MMA(0, 1, At, B1); PG8_BAR; PG8_SCHED;
	s_add_i32 s64, s64, s30
	v_lshl_add_u64 v[146:147], s[24:25], 0, v[158:159]
	s_mov_b32 m0, s64
	ds_read_b128 v[212:215], v177 offset:16384
	ds_read_b128 v[216:219], v177 offset:17408
	ds_read_b128 v[220:223], v177 offset:18432
	ds_read_b128 v[224:227], v177 offset:19456
	ds_read_b128 v[228:231], v177 offset:20480
	ds_read_b128 v[232:235], v177 offset:21504
	ds_read_b128 v[236:239], v177 offset:22528
	ds_read_b128 v[240:243], v177 offset:23552
	global_load_lds_dwordx4 v[146:147], off
	s_add_i32 m0, s64, 0x2000
	s_add_u32 s64, s24, 0x40000
	v_lshl_add_u64 v[148:149], s[24:25], 0, v[154:155]
	s_addc_u32 s65, s25, 0
	s_add_i32 s66, s66, s30
	global_load_lds_dwordx4 v[148:149], off
	v_lshl_add_u64 v[172:173], s[64:65], 0, v[158:159]
	s_mov_b32 m0, s66
	v_lshl_add_u64 v[180:181], s[26:27], 0, v[156:157]
	global_load_lds_dwordx4 v[172:173], off
	v_lshl_add_u64 v[172:173], s[64:65], 0, v[154:155]
	s_add_i32 m0, s66, 0x2000
	s_nop 0
	global_load_lds_dwordx4 v[172:173], off
	v_lshl_add_u64 v[172:173], s[26:27], 0, v[160:161]
	s_mov_b32 m0, s50
	s_nop 0
	global_load_lds_dwordx4 v[172:173], off
	s_mov_b32 m0, s51
	s_nop 0
	global_load_lds_dwordx4 v[180:181], off
	s_waitcnt vmcnt(24)
	s_waitcnt lgkmcnt(0)
	s_barrier
	s_setprio 1
	s_waitcnt lgkmcnt(0)
	v_mfma_f32_16x16x32_bf16 v[62:65], v[130:133], v[212:215], 0
	v_mfma_f32_16x16x32_bf16 v[58:61], v[138:141], v[212:215], 0
	v_mfma_f32_16x16x32_bf16 v[50:53], v[130:133], v[220:223], 0
	v_mfma_f32_16x16x32_bf16 v[42:45], v[138:141], v[220:223], 0
	v_mfma_f32_16x16x32_bf16 v[30:33], v[130:133], v[228:231], 0
	v_mfma_f32_16x16x32_bf16 v[26:29], v[138:141], v[228:231], 0
	v_mfma_f32_16x16x32_bf16 v[18:21], v[130:133], v[236:239], 0
	v_mfma_f32_16x16x32_bf16 v[10:13], v[138:141], v[236:239], 0
	v_mfma_f32_16x16x32_bf16 v[62:65], v[134:137], v[216:219], v[62:65]
	v_mfma_f32_16x16x32_bf16 v[58:61], v[142:145], v[216:219], v[58:61]
	v_mfma_f32_16x16x32_bf16 v[50:53], v[134:137], v[224:227], v[50:53]
	v_mfma_f32_16x16x32_bf16 v[42:45], v[142:145], v[224:227], v[42:45]
	v_mfma_f32_16x16x32_bf16 v[30:33], v[134:137], v[232:235], v[30:33]
	v_mfma_f32_16x16x32_bf16 v[26:29], v[142:145], v[232:235], v[26:29]
	v_mfma_f32_16x16x32_bf16 v[18:21], v[134:137], v[240:243], v[18:21]
	v_mfma_f32_16x16x32_bf16 v[10:13], v[142:145], v[240:243], v[10:13]
	s_setprio 0
	s_setprio 1
	v_mfma_f32_16x16x32_bf16 v[54:57], v[168:171], v[212:215], 0
	v_mfma_f32_16x16x32_bf16 v[46:49], v[204:207], v[212:215], 0
	v_mfma_f32_16x16x32_bf16 v[38:41], v[168:171], v[220:223], 0
	v_mfma_f32_16x16x32_bf16 v[34:37], v[204:207], v[220:223], 0
	v_mfma_f32_16x16x32_bf16 v[22:25], v[168:171], v[228:231], 0
	v_mfma_f32_16x16x32_bf16 v[14:17], v[204:207], v[228:231], 0
	v_mfma_f32_16x16x32_bf16 v[6:9], v[168:171], v[236:239], 0
	v_mfma_f32_16x16x32_bf16 v[2:5], v[204:207], v[236:239], 0
	v_mfma_f32_16x16x32_bf16 v[54:57], v[200:203], v[216:219], v[54:57]
	v_mfma_f32_16x16x32_bf16 v[46:49], v[208:211], v[216:219], v[46:49]
	v_mfma_f32_16x16x32_bf16 v[38:41], v[200:203], v[224:227], v[38:41]
	v_mfma_f32_16x16x32_bf16 v[34:37], v[208:211], v[224:227], v[34:37]
	v_mfma_f32_16x16x32_bf16 v[22:25], v[200:203], v[232:235], v[22:25]
	v_mfma_f32_16x16x32_bf16 v[14:17], v[208:211], v[232:235], v[14:17]
	v_mfma_f32_16x16x32_bf16 v[6:9], v[200:203], v[240:243], v[6:9]
	v_mfma_f32_16x16x32_bf16 v[2:5], v[208:211], v[240:243], v[2:5]
	s_setprio 0
	s_barrier
	s_add_i32 s64, 0, 0x18000
	v_add_u32_e32 v0, s64, v175
	s_add_i32 s65, 0, 0x1c000
	ds_read_b128 v[130:133], v0
	ds_read_b128 v[134:137], v0 offset:1024
	ds_read_b128 v[138:141], v0 offset:2048
	ds_read_b128 v[142:145], v0 offset:3072
	v_add_u32_e32 v0, s65, v175
	ds_read_b128 v[168:171], v0
	ds_read_b128 v[200:203], v0 offset:1024
	ds_read_b128 v[204:207], v0 offset:2048
	ds_read_b128 v[208:211], v0 offset:3072
	s_add_u32 s26, s26, 0x40000
	s_addc_u32 s27, s27, 0
	s_mov_b32 m0, s52
	v_lshl_add_u64 v[244:245], s[26:27], 0, v[160:161]
	ds_read_b128 v[212:215], v177 offset:32768
	ds_read_b128 v[216:219], v177 offset:33792
	ds_read_b128 v[220:223], v177 offset:34816
	ds_read_b128 v[224:227], v177 offset:35840
	ds_read_b128 v[228:231], v177 offset:36864
	ds_read_b128 v[232:235], v177 offset:37888
	ds_read_b128 v[236:239], v177 offset:38912
	ds_read_b128 v[240:243], v177 offset:39936
	global_load_lds_dwordx4 v[244:245], off
	v_lshl_add_u64 v[244:245], s[26:27], 0, v[156:157]
	s_mov_b32 m0, s53
	s_nop 0
	global_load_lds_dwordx4 v[244:245], off
	s_waitcnt vmcnt(8)
	s_waitcnt lgkmcnt(0)
	s_barrier
; #define PG8_STAGE(bufoff, gbase, voff) do { _Pragma("unroll") for (int _i = 0; _i < 2; ++_i) \
;         __builtin_amdgcn_global_load_lds((const unsigned*)((const char*)(gbase) + (voff)[_i]), (PG8_LAS unsigned*)(lds + (bufoff) + ldsw + _i * 8192), 16, 0, 0); } while (0)
; #define PG8_LDA(dst, b, h) do { _Pragma("unroll") for (int m = 0; m < 4; ++m) _Pragma("unroll") for (int k = 0; k < 2; ++k) dst[m][k] = *(const PG8_LAS bf16x8*)(lds + PG8_SA(b, h) + aoff + m * 2048 + k * 1024); } while (0)
; #define PG8_MMA(ai, bj, At, Bt) do { __builtin_amdgcn_s_setprio(1); _Pragma("unroll") for (int m = 0; m < 4; ++m) _Pragma("unroll") for (int n = 0; n < 2; ++n) _Pragma("unroll") for (int k = 0; k < 2; ++k) \
;         acc[ai][bj][m][n] = __builtin_amdgcn_mfma_f32_16x16x32_bf16(Bt[n][k], At[m][k], acc[ai][bj][m][n], 0, 0, 0); __builtin_amdgcn_s_setprio(0); } while (0)
; #define PG8_WAIT_V(n) asm volatile("s_waitcnt vmcnt(" #n ")" ::: "memory")
; #define PG8_WAIT_L(n) asm volatile("s_waitcnt lgkmcnt(" #n ")" ::: "memory")
; #define PG8_BAR __builtin_amdgcn_s_barrier()
; #define PG8_SCHED __builtin_amdgcn_sched_barrier(0)
; template <class Epi, class Sched, bool ALIGN_EPI = false, bool SP2 = false>
; __device__ __forceinline__ void gemm_phase(PG8_LAS unsigned char* lds, const Gemm g, const Sched& S, const Epi& E) {
;     ...
;             PG8_WAIT_V(8); PG8_WAIT_L(0); PG8_BAR; PG8_MMA(0, 0, At, B0); PG8_MMA(0, 1, At, B1); PG8_BAR; PG8_SCHED;
;             PG8_LDA(At, 1, 1); PG8_STAGE(PG8_SB(1, 0), b3, voffB); PG8_STAGE(PG8_SB(1, 1), b3 + hstep, voffB); PG8_STAGE(PG8_SA(1, 0), a3, voffA);
;             PG8_WAIT_V(8); PG8_WAIT_L(0); PG8_BAR; PG8_MMA(1, 0, At, B0); PG8_MMA(1, 1, At, B1); PG8_BAR; PG8_SCHED;
	s_setprio 1
	s_waitcnt lgkmcnt(0)
	v_mfma_f32_16x16x32_bf16 v[126:129], v[130:133], v[212:215], v[126:129]
	v_mfma_f32_16x16x32_bf16 v[122:125], v[138:141], v[212:215], v[122:125]
	v_mfma_f32_16x16x32_bf16 v[114:117], v[130:133], v[220:223], v[114:117]
	v_mfma_f32_16x16x32_bf16 v[106:109], v[138:141], v[220:223], v[106:109]
	v_mfma_f32_16x16x32_bf16 v[94:97], v[130:133], v[228:231], v[94:97]
	v_mfma_f32_16x16x32_bf16 v[90:93], v[138:141], v[228:231], v[90:93]
	v_mfma_f32_16x16x32_bf16 v[82:85], v[130:133], v[236:239], v[82:85]
	v_mfma_f32_16x16x32_bf16 v[74:77], v[138:141], v[236:239], v[74:77]
	v_mfma_f32_16x16x32_bf16 v[126:129], v[134:137], v[216:219], v[126:129]
	v_mfma_f32_16x16x32_bf16 v[122:125], v[142:145], v[216:219], v[122:125]
	v_mfma_f32_16x16x32_bf16 v[114:117], v[134:137], v[224:227], v[114:117]
	v_mfma_f32_16x16x32_bf16 v[106:109], v[142:145], v[224:227], v[106:109]
	v_mfma_f32_16x16x32_bf16 v[94:97], v[134:137], v[232:235], v[94:97]
	v_mfma_f32_16x16x32_bf16 v[90:93], v[142:145], v[232:235], v[90:93]
	v_mfma_f32_16x16x32_bf16 v[82:85], v[134:137], v[240:243], v[82:85]
	v_mfma_f32_16x16x32_bf16 v[74:77], v[142:145], v[240:243], v[74:77]
	s_setprio 0
	s_setprio 1
	v_mfma_f32_16x16x32_bf16 v[118:121], v[168:171], v[212:215], v[118:121]
	v_mfma_f32_16x16x32_bf16 v[110:113], v[204:207], v[212:215], v[110:113]
	v_mfma_f32_16x16x32_bf16 v[102:105], v[168:171], v[220:223], v[102:105]
	v_mfma_f32_16x16x32_bf16 v[98:101], v[204:207], v[220:223], v[98:101]
	v_mfma_f32_16x16x32_bf16 v[86:89], v[168:171], v[228:231], v[86:89]
	v_mfma_f32_16x16x32_bf16 v[78:81], v[204:207], v[228:231], v[78:81]
	v_mfma_f32_16x16x32_bf16 v[70:73], v[168:171], v[236:239], v[70:73]
	v_mfma_f32_16x16x32_bf16 v[66:69], v[204:207], v[236:239], v[66:69]
	v_mfma_f32_16x16x32_bf16 v[118:121], v[200:203], v[216:219], v[118:121]
	v_mfma_f32_16x16x32_bf16 v[110:113], v[208:211], v[216:219], v[110:113]
	v_mfma_f32_16x16x32_bf16 v[102:105], v[200:203], v[224:227], v[102:105]
	v_mfma_f32_16x16x32_bf16 v[98:101], v[208:211], v[224:227], v[98:101]
	v_mfma_f32_16x16x32_bf16 v[86:89], v[200:203], v[232:235], v[86:89]
	v_mfma_f32_16x16x32_bf16 v[78:81], v[208:211], v[232:235], v[78:81]
	v_mfma_f32_16x16x32_bf16 v[70:73], v[200:203], v[240:243], v[70:73]
	v_mfma_f32_16x16x32_bf16 v[66:69], v[208:211], v[240:243], v[66:69]
	s_setprio 0
	s_barrier
	s_add_i32 s26, s64, s30
	v_lshl_add_u64 v[146:147], v[146:147], 0, s[38:39]
	s_mov_b32 m0, s26
	ds_read_b128 v[212:215], v177 offset:49152
	ds_read_b128 v[216:219], v177 offset:50176
	ds_read_b128 v[220:223], v177 offset:51200
	ds_read_b128 v[224:227], v177 offset:52224
	ds_read_b128 v[228:231], v177 offset:53248
	ds_read_b128 v[232:235], v177 offset:54272
	ds_read_b128 v[236:239], v177 offset:55296
	ds_read_b128 v[240:243], v177 offset:56320
	global_load_lds_dwordx4 v[146:147], off
	s_add_i32 m0, s26, 0x2000
	s_add_u32 s24, s24, 0x40080
	v_lshl_add_u64 v[146:147], v[148:149], 0, s[38:39]
	s_addc_u32 s25, s25, 0
	s_add_i32 s26, s65, s30
	global_load_lds_dwordx4 v[146:147], off
	v_lshl_add_u64 v[146:147], s[24:25], 0, v[158:159]
	s_mov_b32 m0, s26
	s_nop 0
	global_load_lds_dwordx4 v[146:147], off
	v_lshl_add_u64 v[146:147], s[24:25], 0, v[154:155]
	s_add_i32 m0, s26, 0x2000
	s_nop 0
	global_load_lds_dwordx4 v[146:147], off
	v_lshl_add_u64 v[146:147], v[172:173], 0, s[38:39]
	s_mov_b32 m0, s55
	s_nop 0
	global_load_lds_dwordx4 v[146:147], off
	v_lshl_add_u64 v[146:147], v[180:181], 0, s[38:39]
	s_mov_b32 m0, s56
	s_nop 0
	global_load_lds_dwordx4 v[146:147], off
	s_waitcnt vmcnt(8)
	s_waitcnt lgkmcnt(0)
	s_barrier
	s_setprio 1
	s_waitcnt lgkmcnt(0)
	v_mfma_f32_16x16x32_bf16 v[62:65], v[130:133], v[212:215], v[62:65]
	v_mfma_f32_16x16x32_bf16 v[58:61], v[138:141], v[212:215], v[58:61]
	v_mfma_f32_16x16x32_bf16 v[50:53], v[130:133], v[220:223], v[50:53]
	v_mfma_f32_16x16x32_bf16 v[42:45], v[138:141], v[220:223], v[42:45]
	v_mfma_f32_16x16x32_bf16 v[30:33], v[130:133], v[228:231], v[30:33]
	v_mfma_f32_16x16x32_bf16 v[26:29], v[138:141], v[228:231], v[26:29]
	v_mfma_f32_16x16x32_bf16 v[18:21], v[130:133], v[236:239], v[18:21]
	v_mfma_f32_16x16x32_bf16 v[10:13], v[138:141], v[236:239], v[10:13]
	v_mfma_f32_16x16x32_bf16 v[62:65], v[134:137], v[216:219], v[62:65]
	v_mfma_f32_16x16x32_bf16 v[58:61], v[142:145], v[216:219], v[58:61]
	v_mfma_f32_16x16x32_bf16 v[50:53], v[134:137], v[224:227], v[50:53]
	v_mfma_f32_16x16x32_bf16 v[42:45], v[142:145], v[224:227], v[42:45]
	v_mfma_f32_16x16x32_bf16 v[30:33], v[134:137], v[232:235], v[30:33]
	v_mfma_f32_16x16x32_bf16 v[26:29], v[142:145], v[232:235], v[26:29]
	v_mfma_f32_16x16x32_bf16 v[18:21], v[134:137], v[240:243], v[18:21]
	v_mfma_f32_16x16x32_bf16 v[10:13], v[142:145], v[240:243], v[10:13]
	s_setprio 0
	s_setprio 1
	v_mfma_f32_16x16x32_bf16 v[54:57], v[168:171], v[212:215], v[54:57]
	v_mfma_f32_16x16x32_bf16 v[46:49], v[204:207], v[212:215], v[46:49]
	v_mfma_f32_16x16x32_bf16 v[38:41], v[168:171], v[220:223], v[38:41]
	v_mfma_f32_16x16x32_bf16 v[34:37], v[204:207], v[220:223], v[34:37]
	v_mfma_f32_16x16x32_bf16 v[22:25], v[168:171], v[228:231], v[22:25]
	v_mfma_f32_16x16x32_bf16 v[14:17], v[204:207], v[228:231], v[14:17]
	v_mfma_f32_16x16x32_bf16 v[6:9], v[168:171], v[236:239], v[6:9]
	v_mfma_f32_16x16x32_bf16 v[2:5], v[204:207], v[236:239], v[2:5]
	v_mfma_f32_16x16x32_bf16 v[54:57], v[200:203], v[216:219], v[54:57]
	v_mfma_f32_16x16x32_bf16 v[46:49], v[208:211], v[216:219], v[46:49]
	v_mfma_f32_16x16x32_bf16 v[38:41], v[200:203], v[224:227], v[38:41]
	v_mfma_f32_16x16x32_bf16 v[34:37], v[208:211], v[224:227], v[34:37]
	v_mfma_f32_16x16x32_bf16 v[22:25], v[200:203], v[232:235], v[22:25]
	v_mfma_f32_16x16x32_bf16 v[14:17], v[208:211], v[232:235], v[14:17]
	v_mfma_f32_16x16x32_bf16 v[6:9], v[200:203], v[240:243], v[6:9]
	v_mfma_f32_16x16x32_bf16 v[2:5], v[208:211], v[240:243], v[2:5]
	s_setprio 0
	s_barrier
	s_add_i32 s63, s63, 2
	s_add_u32 s22, s22, 0x100
	s_addc_u32 s23, s23, 0
	s_add_u32 s61, s61, 0x100
	s_addc_u32 s62, s62, 0

;     __device__ __forceinline__ void operator()(const f32x4 (&acc)[2][2][4][2], const Unit& u, int wr, int wc, int fr, int fq) const {
;     ...
;         } else if (u.pn == nmain) {
;             if (wc == 0 && fq < 2) {
; #pragma unroll
;                 for (int ai = 0; ai < 2; ++ai)
; #pragma unroll
;                     for (int m = 0; m < 4; ++m) { float* gp = G + (size_t)(row0 + ai * HALF + m * 16) * 16 + 8 * fq;
;                         *(f32x4*)gp = acc[ai][0][m][0]; *(f32x4*)(gp + 4) = acc[ai][0][m][1]; }
;             }
;         }
.LBB0_567:
	s_or_b64 exec, exec, s[20:21]
	s_mov_b64 s[20:21], 0
	s_waitcnt vmcnt(0)

; #define PG8_STAGE(bufoff, gbase, voff) do { _Pragma("unroll") for (int _i = 0; _i < 2; ++_i) \
;         __builtin_amdgcn_global_load_lds((const unsigned*)((const char*)(gbase) + (voff)[_i]), (PG8_LAS unsigned*)(lds + (bufoff) + ldsw + _i * 8192), 16, 0, 0); } while (0)
; #define PG8_LDA(dst, b, h) do { _Pragma("unroll") for (int m = 0; m < 4; ++m) _Pragma("unroll") for (int k = 0; k < 2; ++k) dst[m][k] = *(const PG8_LAS bf16x8*)(lds + PG8_SA(b, h) + aoff + m * 2048 + k * 1024); } while (0)
; #define PG8_LDB(dst, b, h) do { _Pragma("unroll") for (int n = 0; n < 2; ++n) _Pragma("unroll") for (int k = 0; k < 2; ++k) dst[n][k] = *(const PG8_LAS bf16x8*)(lds + PG8_SB(b, h) + boff + n * 2048 + k * 1024); } while (0)
; #define PG8_SCHED __builtin_amdgcn_sched_barrier(0)
;     __host__ __device__ bool next(int i, Unit& u) const {
;         const long L = (long)i * G + c; if (L >= nwg) return false;
;         int wgid = (int)L; { const int q = nwg / NXCD, r = nwg % NXCD, xcd = wgid % NXCD, off = wgid / NXCD; wgid = (xcd < r ? xcd * (q + 1) : r * (q + 1) + (xcd - r) * q) + off; }
;         const int nig = WGM * nN, gid = wgid / nig, fm = gid * WGM, gsz = (nM - fm) < WGM ? (nM - fm) : WGM;
;         u.pm = fm + ((wgid % nig) % gsz); u.pn = (wgid % nig) / gsz; return true;
;     }
; template <class Epi, class Sched, bool ALIGN_EPI = false, bool SP2 = false>
; __device__ __forceinline__ void gemm_phase(PG8_LAS unsigned char* lds, const Gemm g, const Sched& S, const Epi& E) {
;     ...
;             PG8_LDB(B0, 0, 0); PG8_LDB(B1, 0, 1); PG8_SCHED; PG8_LDA(At, 0, 0); PG8_STAGE(PG8_SA(1, 1), a1 + hstep, voffA);
.LBB0_1083:
	v_add_u32_e32 v148, 0x10000, v167
	ds_read_b128 v[140:143], v148
	ds_read_b128 v[144:147], v148 offset:1024
	ds_read_b128 v[154:157], v148 offset:2048
	ds_read_b128 v[158:161], v148 offset:3072
	v_add_u32_e32 v148, 0x14000, v167
	ds_read_b128 v[162:165], v148
	ds_read_b128 v[170:173], v148 offset:1024
	ds_read_b128 v[174:177], v148 offset:2048
	ds_read_b128 v[178:181], v148 offset:3072
	ds_read_b128 v[200:203], v169
	ds_read_b128 v[204:207], v169 offset:1024
	ds_read_b128 v[208:211], v169 offset:2048
	ds_read_b128 v[212:215], v169 offset:3072
	ds_read_b128 v[216:219], v169 offset:4096
	ds_read_b128 v[220:223], v169 offset:5120
	ds_read_b128 v[224:227], v169 offset:6144
	ds_read_b128 v[228:231], v169 offset:7168
	s_add_i32 s34, s34, 1
	s_mul_i32 s4, s34, s79
	s_mul_hi_u32 s5, s34, s78
	s_add_i32 s5, s5, s4
	s_mul_i32 s4, s34, s78
	s_add_u32 s12, s4, s2
	s_addc_u32 s13, s5, s3
	v_cmp_gt_i64_e32 vcc, s[12:13], v[152:153]
	v_cmp_lt_i64_e64 s[4:5], s[12:13], v[150:151]
	s_cbranch_vccnz .LBB0_1089
	s_ashr_i32 s8, s12, 31
	s_lshr_b32 s8, s8, 29
	s_add_i32 s10, s12, s8
	s_and_b32 s8, s10, -8
	s_sub_i32 s11, s12, s8
	s_cmp_gt_i32 s11, -1
	s_mov_b64 s[8:9], -1
	s_cbranch_scc0 .LBB0_1086
	s_lshl_b32 s12, s11, 6
	s_mov_b64 s[8:9], 0

; #define PG8_STAGE(bufoff, gbase, voff) do { _Pragma("unroll") for (int _i = 0; _i < 2; ++_i) \
;         __builtin_amdgcn_global_load_lds((const unsigned*)((const char*)(gbase) + (voff)[_i]), (PG8_LAS unsigned*)(lds + (bufoff) + ldsw + _i * 8192), 16, 0, 0); } while (0)
; #define PG8_LDA(dst, b, h) do { _Pragma("unroll") for (int m = 0; m < 4; ++m) _Pragma("unroll") for (int k = 0; k < 2; ++k) dst[m][k] = *(const PG8_LAS bf16x8*)(lds + PG8_SA(b, h) + aoff + m * 2048 + k * 1024); } while (0)
; #define PG8_LDB(dst, b, h) do { _Pragma("unroll") for (int n = 0; n < 2; ++n) _Pragma("unroll") for (int k = 0; k < 2; ++k) dst[n][k] = *(const PG8_LAS bf16x8*)(lds + PG8_SB(b, h) + boff + n * 2048 + k * 1024); } while (0)
; #define PG8_WAIT_V(n) asm volatile("s_waitcnt vmcnt(" #n ")" ::: "memory")
; #define PG8_WAIT_L(n) asm volatile("s_waitcnt lgkmcnt(" #n ")" ::: "memory")
; #define PG8_BAR __builtin_amdgcn_s_barrier()
; #define PG8_SCHED __builtin_amdgcn_sched_barrier(0)
; template <class Epi, class Sched, bool ALIGN_EPI = false, bool SP2 = false>
; __device__ __forceinline__ void gemm_phase(PG8_LAS unsigned char* lds, const Gemm g, const Sched& S, const Epi& E) {
;     ...
;         const bool has_next = S.next(ui + 1, nxt);
;         const char* nA = has_next ? (const char*)g.A + (size_t)nxt.pm * tstep : cA; const char* nB = has_next ? (const char*)g.Bt + (size_t)nxt.pn * tstep : cB;
;         for (int t = 0; t < nt; t += 2) {
;             const bool last = (t == nt - 2);
;             const char* a1 = cA + (size_t)(t + 1) * kstep;
;             const char* a2 = last ? nA : cA + (size_t)(t + 2) * kstep; const char* b2 = last ? nB : cB + (size_t)(t + 2) * kstep;
;             const char* a3 = a2 + kstep; const char* b3 = b2 + kstep;
;             if (last && has_next) S.a_ready(nxt);
;             if constexpr (SP2) {
;             PG8_LDB(B0, 0, 0); PG8_LDB(B1, 0, 1); PG8_SCHED; PG8_LDA(At, 0, 0); PG8_STAGE(PG8_SA(1, 1), a1 + hstep, voffA);
;             PG8_WAIT_V(8); PG8_WAIT_L(0); PG8_BAR; PG8_MMA(0, 0, At, B0); PG8_MMA(0, 1, At, B1); PG8_BAR; PG8_SCHED;
;             PG8_LDA(At, 0, 1); PG8_STAGE(PG8_SB(0, 0), b2, voffB); PG8_STAGE(PG8_SB(0, 1), b2 + hstep, voffB); PG8_STAGE(PG8_SA(0, 0), a2, voffA);
;             PG8_WAIT_V(8); PG8_WAIT_L(0); PG8_BAR; PG8_MMA(1, 0, At, B0); PG8_MMA(1, 1, At, B1); PG8_BAR; PG8_SCHED;
.LBB0_1089:
	s_ashr_i32 s11, s10, 31
	s_lshl_b64 s[12:13], s[10:11], 19
	s_add_u32 s12, s90, s12
	s_addc_u32 s13, s91, s13
	s_and_b64 s[14:15], s[4:5], exec
	s_cselect_b32 s11, s13, s17
	s_cselect_b32 s45, s12, s16
	s_ashr_i32 s9, s8, 31
	s_lshl_b64 s[14:15], s[8:9], 19
	s_add_u32 s14, s22, s14
	s_addc_u32 s15, s23, s15
	s_and_b64 s[20:21], s[4:5], exec
	s_cselect_b32 s9, s15, s19
	s_cselect_b32 s46, s14, s18
	s_add_u32 s16, s16, 0x40080
	s_addc_u32 s17, s17, 0
	s_add_u32 s47, s18, 0x100
	s_addc_u32 s48, s19, 0
	s_mov_b32 s49, -2
	s_add_u32 s18, s16, 0xfffc0080
	s_addc_u32 s19, s17, -1
	s_add_i32 s50, 0, 0x10000
	s_cmp_eq_u32 s49, 12
	s_cselect_b32 s21, s11, s19
	s_cselect_b32 s20, s45, s18
	s_cselect_b32 s19, s9, s48
	s_cselect_b32 s18, s46, s47
	s_add_i32 s52, 0, 0x14000
	v_lshl_add_u64 v[148:149], s[16:17], 0, v[136:137]
	s_add_i32 m0, s25, 0xc000
	global_load_lds_dwordx4 v[148:149], off
	v_lshl_add_u64 v[148:149], s[16:17], 0, v[138:139]
	s_add_i32 m0, s25, 0xe000
	s_nop 0
	global_load_lds_dwordx4 v[148:149], off
	s_waitcnt vmcnt(20)
	s_waitcnt lgkmcnt(0)
	s_barrier
	s_setprio 1
	s_waitcnt lgkmcnt(0)
	v_mfma_f32_16x16x32_bf16 v[126:129], v[140:143], v[200:203], 0
	v_mfma_f32_16x16x32_bf16 v[122:125], v[154:157], v[200:203], 0
	v_mfma_f32_16x16x32_bf16 v[118:121], v[140:143], v[208:211], 0
	v_mfma_f32_16x16x32_bf16 v[114:117], v[154:157], v[208:211], 0
	v_mfma_f32_16x16x32_bf16 v[110:113], v[140:143], v[216:219], 0
	v_mfma_f32_16x16x32_bf16 v[106:109], v[154:157], v[216:219], 0
	v_mfma_f32_16x16x32_bf16 v[102:105], v[140:143], v[224:227], 0
	v_mfma_f32_16x16x32_bf16 v[98:101], v[154:157], v[224:227], 0
	v_mfma_f32_16x16x32_bf16 v[126:129], v[144:147], v[204:207], v[126:129]
	v_mfma_f32_16x16x32_bf16 v[122:125], v[158:161], v[204:207], v[122:125]
	v_mfma_f32_16x16x32_bf16 v[118:121], v[144:147], v[212:215], v[118:121]
	v_mfma_f32_16x16x32_bf16 v[114:117], v[158:161], v[212:215], v[114:117]
	v_mfma_f32_16x16x32_bf16 v[110:113], v[144:147], v[220:223], v[110:113]
	v_mfma_f32_16x16x32_bf16 v[106:109], v[158:161], v[220:223], v[106:109]
	v_mfma_f32_16x16x32_bf16 v[102:105], v[144:147], v[228:231], v[102:105]
	v_mfma_f32_16x16x32_bf16 v[98:101], v[158:161], v[228:231], v[98:101]
	s_setprio 0
	s_setprio 1
	v_mfma_f32_16x16x32_bf16 v[62:65], v[162:165], v[200:203], 0
	v_mfma_f32_16x16x32_bf16 v[58:61], v[174:177], v[200:203], 0
	v_mfma_f32_16x16x32_bf16 v[54:57], v[162:165], v[208:211], 0
	v_mfma_f32_16x16x32_bf16 v[50:53], v[174:177], v[208:211], 0
	v_mfma_f32_16x16x32_bf16 v[46:49], v[162:165], v[216:219], 0
	v_mfma_f32_16x16x32_bf16 v[42:45], v[174:177], v[216:219], 0
	v_mfma_f32_16x16x32_bf16 v[38:41], v[162:165], v[224:227], 0
	v_mfma_f32_16x16x32_bf16 v[34:37], v[174:177], v[224:227], 0
	v_mfma_f32_16x16x32_bf16 v[62:65], v[170:173], v[204:207], v[62:65]
	v_mfma_f32_16x16x32_bf16 v[58:61], v[178:181], v[204:207], v[58:61]
	v_mfma_f32_16x16x32_bf16 v[54:57], v[170:173], v[212:215], v[54:57]
	v_mfma_f32_16x16x32_bf16 v[50:53], v[178:181], v[212:215], v[50:53]
	v_mfma_f32_16x16x32_bf16 v[46:49], v[170:173], v[220:223], v[46:49]
	v_mfma_f32_16x16x32_bf16 v[42:45], v[178:181], v[220:223], v[42:45]
	v_mfma_f32_16x16x32_bf16 v[38:41], v[170:173], v[228:231], v[38:41]
	v_mfma_f32_16x16x32_bf16 v[34:37], v[178:181], v[228:231], v[34:37]
	s_setprio 0
	s_barrier
	s_add_i32 s50, s50, s24
	v_lshl_add_u64 v[148:149], s[18:19], 0, v[0:1]
	s_mov_b32 m0, s50
	ds_read_b128 v[200:203], v169 offset:16384
	ds_read_b128 v[204:207], v169 offset:17408
	ds_read_b128 v[208:211], v169 offset:18432
	ds_read_b128 v[212:215], v169 offset:19456
	ds_read_b128 v[216:219], v169 offset:20480
	ds_read_b128 v[220:223], v169 offset:21504
	ds_read_b128 v[224:227], v169 offset:22528
	ds_read_b128 v[228:231], v169 offset:23552
	global_load_lds_dwordx4 v[148:149], off
	s_add_i32 m0, s50, 0x2000
	s_add_u32 s50, s18, 0x40000
	v_lshl_add_u64 v[232:233], s[18:19], 0, v[130:131]
	s_addc_u32 s51, s19, 0
	s_add_i32 s52, s52, s24
	global_load_lds_dwordx4 v[232:233], off
	v_lshl_add_u64 v[234:235], s[50:51], 0, v[0:1]
	s_mov_b32 m0, s52
	v_lshl_add_u64 v[236:237], s[20:21], 0, v[132:133]
	global_load_lds_dwordx4 v[234:235], off
	v_lshl_add_u64 v[234:235], s[50:51], 0, v[130:131]
	s_add_i32 m0, s52, 0x2000
	s_nop 0
	global_load_lds_dwordx4 v[234:235], off
	v_lshl_add_u64 v[234:235], s[20:21], 0, v[134:135]
	s_mov_b32 m0, s25
	s_nop 0
	global_load_lds_dwordx4 v[234:235], off
	s_mov_b32 m0, s26
	s_nop 0
	global_load_lds_dwordx4 v[236:237], off
	s_waitcnt vmcnt(20)
	s_waitcnt lgkmcnt(0)
	s_barrier
	s_setprio 1
	s_waitcnt lgkmcnt(0)
	v_mfma_f32_16x16x32_bf16 v[94:97], v[140:143], v[200:203], 0
	v_mfma_f32_16x16x32_bf16 v[90:93], v[154:157], v[200:203], 0
	v_mfma_f32_16x16x32_bf16 v[86:89], v[140:143], v[208:211], 0
	v_mfma_f32_16x16x32_bf16 v[82:85], v[154:157], v[208:211], 0
	v_mfma_f32_16x16x32_bf16 v[78:81], v[140:143], v[216:219], 0
	v_mfma_f32_16x16x32_bf16 v[74:77], v[154:157], v[216:219], 0
	v_mfma_f32_16x16x32_bf16 v[70:73], v[140:143], v[224:227], 0
	v_mfma_f32_16x16x32_bf16 v[66:69], v[154:157], v[224:227], 0
	v_mfma_f32_16x16x32_bf16 v[94:97], v[144:147], v[204:207], v[94:97]
	v_mfma_f32_16x16x32_bf16 v[90:93], v[158:161], v[204:207], v[90:93]
	v_mfma_f32_16x16x32_bf16 v[86:89], v[144:147], v[212:215], v[86:89]
	v_mfma_f32_16x16x32_bf16 v[82:85], v[158:161], v[212:215], v[82:85]
	v_mfma_f32_16x16x32_bf16 v[78:81], v[144:147], v[220:223], v[78:81]
	v_mfma_f32_16x16x32_bf16 v[74:77], v[158:161], v[220:223], v[74:77]
	v_mfma_f32_16x16x32_bf16 v[70:73], v[144:147], v[228:231], v[70:73]
	v_mfma_f32_16x16x32_bf16 v[66:69], v[158:161], v[228:231], v[66:69]
	s_setprio 0
	s_setprio 1
	v_mfma_f32_16x16x32_bf16 v[30:33], v[162:165], v[200:203], 0
	v_mfma_f32_16x16x32_bf16 v[26:29], v[174:177], v[200:203], 0
	v_mfma_f32_16x16x32_bf16 v[22:25], v[162:165], v[208:211], 0
	v_mfma_f32_16x16x32_bf16 v[18:21], v[174:177], v[208:211], 0
	v_mfma_f32_16x16x32_bf16 v[14:17], v[162:165], v[216:219], 0
	v_mfma_f32_16x16x32_bf16 v[10:13], v[174:177], v[216:219], 0
	v_mfma_f32_16x16x32_bf16 v[6:9], v[162:165], v[224:227], 0
	v_mfma_f32_16x16x32_bf16 v[2:5], v[174:177], v[224:227], 0
	v_mfma_f32_16x16x32_bf16 v[30:33], v[170:173], v[204:207], v[30:33]
	v_mfma_f32_16x16x32_bf16 v[26:29], v[178:181], v[204:207], v[26:29]
	v_mfma_f32_16x16x32_bf16 v[22:25], v[170:173], v[212:215], v[22:25]
	v_mfma_f32_16x16x32_bf16 v[18:21], v[178:181], v[212:215], v[18:21]
	v_mfma_f32_16x16x32_bf16 v[14:17], v[170:173], v[220:223], v[14:17]
	v_mfma_f32_16x16x32_bf16 v[10:13], v[178:181], v[220:223], v[10:13]
	v_mfma_f32_16x16x32_bf16 v[6:9], v[170:173], v[228:231], v[6:9]
	v_mfma_f32_16x16x32_bf16 v[2:5], v[178:181], v[228:231], v[2:5]
	s_setprio 0
	s_barrier
; #define PG8_STAGE(bufoff, gbase, voff) do { _Pragma("unroll") for (int _i = 0; _i < 2; ++_i) \
;         __builtin_amdgcn_global_load_lds((const unsigned*)((const char*)(gbase) + (voff)[_i]), (PG8_LAS unsigned*)(lds + (bufoff) + ldsw + _i * 8192), 16, 0, 0); } while (0)
; #define PG8_LDA(dst, b, h) do { _Pragma("unroll") for (int m = 0; m < 4; ++m) _Pragma("unroll") for (int k = 0; k < 2; ++k) dst[m][k] = *(const PG8_LAS bf16x8*)(lds + PG8_SA(b, h) + aoff + m * 2048 + k * 1024); } while (0)
; #define PG8_LDB(dst, b, h) do { _Pragma("unroll") for (int n = 0; n < 2; ++n) _Pragma("unroll") for (int k = 0; k < 2; ++k) dst[n][k] = *(const PG8_LAS bf16x8*)(lds + PG8_SB(b, h) + boff + n * 2048 + k * 1024); } while (0)
; #define PG8_MMA(ai, bj, At, Bt) do { __builtin_amdgcn_s_setprio(1); _Pragma("unroll") for (int m = 0; m < 4; ++m) _Pragma("unroll") for (int n = 0; n < 2; ++n) _Pragma("unroll") for (int k = 0; k < 2; ++k) \
;         acc[ai][bj][m][n] = __builtin_amdgcn_mfma_f32_16x16x32_bf16(Bt[n][k], At[m][k], acc[ai][bj][m][n], 0, 0, 0); __builtin_amdgcn_s_setprio(0); } while (0)
; #define PG8_WAIT_V(n) asm volatile("s_waitcnt vmcnt(" #n ")" ::: "memory")
; #define PG8_WAIT_L(n) asm volatile("s_waitcnt lgkmcnt(" #n ")" ::: "memory")
; #define PG8_BAR __builtin_amdgcn_s_barrier()
; #define PG8_SCHED __builtin_amdgcn_sched_barrier(0)
; template <class Epi, class Sched, bool ALIGN_EPI = false, bool SP2 = false>
; __device__ __forceinline__ void gemm_phase(PG8_LAS unsigned char* lds, const Gemm g, const Sched& S, const Epi& E) {
;     ...
;             PG8_LDB(B0, 1, 0); PG8_LDB(B1, 1, 1); PG8_SCHED; PG8_LDA(At, 1, 0); PG8_STAGE(PG8_SA(0, 1), a2 + hstep, voffA);
;             PG8_WAIT_V(8); PG8_WAIT_L(0); PG8_BAR; PG8_MMA(0, 0, At, B0); PG8_MMA(0, 1, At, B1); PG8_BAR; PG8_SCHED;
	s_add_i32 s50, 0, 0x18000
	s_add_i32 s51, 0, 0x1c000
	v_add_u32_e32 v158, s50, v167
	v_add_u32_e32 v178, s51, v167
	ds_read_b128 v[140:143], v158
	ds_read_b128 v[144:147], v158 offset:1024
	ds_read_b128 v[154:157], v158 offset:2048
	ds_read_b128 v[158:161], v158 offset:3072
	ds_read_b128 v[162:165], v178
	ds_read_b128 v[170:173], v178 offset:1024
	ds_read_b128 v[174:177], v178 offset:2048
	ds_read_b128 v[178:181], v178 offset:3072
	s_add_u32 s20, s20, 0x40000
	s_addc_u32 s21, s21, 0
	s_mov_b32 m0, s27
	v_lshl_add_u64 v[238:239], s[20:21], 0, v[134:135]
	ds_read_b128 v[200:203], v169 offset:32768
	ds_read_b128 v[204:207], v169 offset:33792
	ds_read_b128 v[208:211], v169 offset:34816
	ds_read_b128 v[212:215], v169 offset:35840
	ds_read_b128 v[216:219], v169 offset:36864
	ds_read_b128 v[220:223], v169 offset:37888
	ds_read_b128 v[224:227], v169 offset:38912
	ds_read_b128 v[228:231], v169 offset:39936
	global_load_lds_dwordx4 v[238:239], off
	v_lshl_add_u64 v[238:239], s[20:21], 0, v[132:133]
	s_mov_b32 m0, s28
	s_nop 0
	global_load_lds_dwordx4 v[238:239], off
	s_waitcnt vmcnt(8)
	s_waitcnt lgkmcnt(0)
	s_barrier
	s_setprio 1
	s_waitcnt lgkmcnt(0)
	v_mfma_f32_16x16x32_bf16 v[126:129], v[140:143], v[200:203], v[126:129]
	v_mfma_f32_16x16x32_bf16 v[122:125], v[154:157], v[200:203], v[122:125]
	v_mfma_f32_16x16x32_bf16 v[118:121], v[140:143], v[208:211], v[118:121]
	v_mfma_f32_16x16x32_bf16 v[114:117], v[154:157], v[208:211], v[114:117]
	v_mfma_f32_16x16x32_bf16 v[110:113], v[140:143], v[216:219], v[110:113]
	v_mfma_f32_16x16x32_bf16 v[106:109], v[154:157], v[216:219], v[106:109]
	v_mfma_f32_16x16x32_bf16 v[102:105], v[140:143], v[224:227], v[102:105]
	v_mfma_f32_16x16x32_bf16 v[98:101], v[154:157], v[224:227], v[98:101]
	v_mfma_f32_16x16x32_bf16 v[126:129], v[144:147], v[204:207], v[126:129]
	v_mfma_f32_16x16x32_bf16 v[122:125], v[158:161], v[204:207], v[122:125]
	v_mfma_f32_16x16x32_bf16 v[118:121], v[144:147], v[212:215], v[118:121]
	v_mfma_f32_16x16x32_bf16 v[114:117], v[158:161], v[212:215], v[114:117]
	v_mfma_f32_16x16x32_bf16 v[110:113], v[144:147], v[220:223], v[110:113]
	v_mfma_f32_16x16x32_bf16 v[106:109], v[158:161], v[220:223], v[106:109]
	v_mfma_f32_16x16x32_bf16 v[102:105], v[144:147], v[228:231], v[102:105]
	v_mfma_f32_16x16x32_bf16 v[98:101], v[158:161], v[228:231], v[98:101]
	s_setprio 0
	s_setprio 1
	v_mfma_f32_16x16x32_bf16 v[62:65], v[162:165], v[200:203], v[62:65]
	v_mfma_f32_16x16x32_bf16 v[58:61], v[174:177], v[200:203], v[58:61]
	v_mfma_f32_16x16x32_bf16 v[54:57], v[162:165], v[208:211], v[54:57]
	v_mfma_f32_16x16x32_bf16 v[50:53], v[174:177], v[208:211], v[50:53]
	v_mfma_f32_16x16x32_bf16 v[46:49], v[162:165], v[216:219], v[46:49]
	v_mfma_f32_16x16x32_bf16 v[42:45], v[174:177], v[216:219], v[42:45]
	v_mfma_f32_16x16x32_bf16 v[38:41], v[162:165], v[224:227], v[38:41]
	v_mfma_f32_16x16x32_bf16 v[34:37], v[174:177], v[224:227], v[34:37]
	v_mfma_f32_16x16x32_bf16 v[62:65], v[170:173], v[204:207], v[62:65]
	v_mfma_f32_16x16x32_bf16 v[58:61], v[178:181], v[204:207], v[58:61]
	v_mfma_f32_16x16x32_bf16 v[54:57], v[170:173], v[212:215], v[54:57]
	v_mfma_f32_16x16x32_bf16 v[50:53], v[178:181], v[212:215], v[50:53]
	v_mfma_f32_16x16x32_bf16 v[46:49], v[170:173], v[220:223], v[46:49]
	v_mfma_f32_16x16x32_bf16 v[42:45], v[178:181], v[220:223], v[42:45]
	v_mfma_f32_16x16x32_bf16 v[38:41], v[170:173], v[228:231], v[38:41]
	v_mfma_f32_16x16x32_bf16 v[34:37], v[178:181], v[228:231], v[34:37]
	s_setprio 0
	s_barrier
; #define PG8_STAGE(bufoff, gbase, voff) do { _Pragma("unroll") for (int _i = 0; _i < 2; ++_i) \
;         __builtin_amdgcn_global_load_lds((const unsigned*)((const char*)(gbase) + (voff)[_i]), (PG8_LAS unsigned*)(lds + (bufoff) + ldsw + _i * 8192), 16, 0, 0); } while (0)
; #define PG8_LDA(dst, b, h) do { _Pragma("unroll") for (int m = 0; m < 4; ++m) _Pragma("unroll") for (int k = 0; k < 2; ++k) dst[m][k] = *(const PG8_LAS bf16x8*)(lds + PG8_SA(b, h) + aoff + m * 2048 + k * 1024); } while (0)
; #define PG8_MMA(ai, bj, At, Bt) do { __builtin_amdgcn_s_setprio(1); _Pragma("unroll") for (int m = 0; m < 4; ++m) _Pragma("unroll") for (int n = 0; n < 2; ++n) _Pragma("unroll") for (int k = 0; k < 2; ++k) \
;         acc[ai][bj][m][n] = __builtin_amdgcn_mfma_f32_16x16x32_bf16(Bt[n][k], At[m][k], acc[ai][bj][m][n], 0, 0, 0); __builtin_amdgcn_s_setprio(0); } while (0)
; #define PG8_WAIT_V(n) asm volatile("s_waitcnt vmcnt(" #n ")" ::: "memory")
; #define PG8_WAIT_L(n) asm volatile("s_waitcnt lgkmcnt(" #n ")" ::: "memory")
; #define PG8_BAR __builtin_amdgcn_s_barrier()
; #define PG8_SCHED __builtin_amdgcn_sched_barrier(0)
; template <class Epi, class Sched, bool ALIGN_EPI = false, bool SP2 = false>
; __device__ __forceinline__ void gemm_phase(PG8_LAS unsigned char* lds, const Gemm g, const Sched& S, const Epi& E) {
;     ...
;         for (int t = 0; t < nt; t += 2) {
;     ...
;             PG8_LDA(At, 1, 1); PG8_STAGE(PG8_SB(1, 0), b3, voffB); PG8_STAGE(PG8_SB(1, 1), b3 + hstep, voffB); PG8_STAGE(PG8_SA(1, 0), a3, voffA);
;             PG8_WAIT_V(8); PG8_WAIT_L(0); PG8_BAR; PG8_MMA(1, 0, At, B0); PG8_MMA(1, 1, At, B1); PG8_BAR; PG8_SCHED;
	s_add_i32 s20, s50, s24
	v_lshl_add_u64 v[148:149], v[148:149], 0, s[38:39]
	s_mov_b32 m0, s20
	ds_read_b128 v[200:203], v169 offset:49152
	ds_read_b128 v[204:207], v169 offset:50176
	ds_read_b128 v[208:211], v169 offset:51200
	ds_read_b128 v[212:215], v169 offset:52224
	ds_read_b128 v[216:219], v169 offset:53248
	ds_read_b128 v[220:223], v169 offset:54272
	ds_read_b128 v[224:227], v169 offset:55296
	ds_read_b128 v[228:231], v169 offset:56320
	global_load_lds_dwordx4 v[148:149], off
	s_add_i32 m0, s20, 0x2000
	s_add_u32 s18, s18, 0x40080
	v_lshl_add_u64 v[148:149], v[232:233], 0, s[38:39]
	s_addc_u32 s19, s19, 0
	s_add_i32 s20, s51, s24
	global_load_lds_dwordx4 v[148:149], off
	v_lshl_add_u64 v[148:149], s[18:19], 0, v[0:1]
	s_mov_b32 m0, s20
	s_nop 0
	global_load_lds_dwordx4 v[148:149], off
	v_lshl_add_u64 v[148:149], s[18:19], 0, v[130:131]
	s_add_i32 m0, s20, 0x2000
	s_nop 0
	global_load_lds_dwordx4 v[148:149], off
	v_lshl_add_u64 v[148:149], v[234:235], 0, s[38:39]
	s_mov_b32 m0, s31
	s_nop 0
	global_load_lds_dwordx4 v[148:149], off
	v_lshl_add_u64 v[148:149], v[236:237], 0, s[38:39]
	s_mov_b32 m0, s33
	s_nop 0
	global_load_lds_dwordx4 v[148:149], off
	s_waitcnt vmcnt(8)
	s_waitcnt lgkmcnt(0)
	s_barrier
	s_setprio 1
	s_waitcnt lgkmcnt(0)
	v_mfma_f32_16x16x32_bf16 v[94:97], v[140:143], v[200:203], v[94:97]
	v_mfma_f32_16x16x32_bf16 v[90:93], v[154:157], v[200:203], v[90:93]
	v_mfma_f32_16x16x32_bf16 v[86:89], v[140:143], v[208:211], v[86:89]
	v_mfma_f32_16x16x32_bf16 v[82:85], v[154:157], v[208:211], v[82:85]
	v_mfma_f32_16x16x32_bf16 v[78:81], v[140:143], v[216:219], v[78:81]
	v_mfma_f32_16x16x32_bf16 v[74:77], v[154:157], v[216:219], v[74:77]
	v_mfma_f32_16x16x32_bf16 v[70:73], v[140:143], v[224:227], v[70:73]
	v_mfma_f32_16x16x32_bf16 v[66:69], v[154:157], v[224:227], v[66:69]
	v_mfma_f32_16x16x32_bf16 v[94:97], v[144:147], v[204:207], v[94:97]
	v_mfma_f32_16x16x32_bf16 v[90:93], v[158:161], v[204:207], v[90:93]
	v_mfma_f32_16x16x32_bf16 v[86:89], v[144:147], v[212:215], v[86:89]
	v_mfma_f32_16x16x32_bf16 v[82:85], v[158:161], v[212:215], v[82:85]
	v_mfma_f32_16x16x32_bf16 v[78:81], v[144:147], v[220:223], v[78:81]
	v_mfma_f32_16x16x32_bf16 v[74:77], v[158:161], v[220:223], v[74:77]
	v_mfma_f32_16x16x32_bf16 v[70:73], v[144:147], v[228:231], v[70:73]
	v_mfma_f32_16x16x32_bf16 v[66:69], v[158:161], v[228:231], v[66:69]
	s_setprio 0
	s_setprio 1
	v_mfma_f32_16x16x32_bf16 v[30:33], v[162:165], v[200:203], v[30:33]
	v_mfma_f32_16x16x32_bf16 v[26:29], v[174:177], v[200:203], v[26:29]
	v_mfma_f32_16x16x32_bf16 v[22:25], v[162:165], v[208:211], v[22:25]
	v_mfma_f32_16x16x32_bf16 v[18:21], v[174:177], v[208:211], v[18:21]
	v_mfma_f32_16x16x32_bf16 v[14:17], v[162:165], v[216:219], v[14:17]
	v_mfma_f32_16x16x32_bf16 v[10:13], v[174:177], v[216:219], v[10:13]
	v_mfma_f32_16x16x32_bf16 v[6:9], v[162:165], v[224:227], v[6:9]
	v_mfma_f32_16x16x32_bf16 v[2:5], v[174:177], v[224:227], v[2:5]
	v_mfma_f32_16x16x32_bf16 v[30:33], v[170:173], v[204:207], v[30:33]
	v_mfma_f32_16x16x32_bf16 v[26:29], v[178:181], v[204:207], v[26:29]
	v_mfma_f32_16x16x32_bf16 v[22:25], v[170:173], v[212:215], v[22:25]
	v_mfma_f32_16x16x32_bf16 v[18:21], v[178:181], v[212:215], v[18:21]
	v_mfma_f32_16x16x32_bf16 v[14:17], v[170:173], v[220:223], v[14:17]
	v_mfma_f32_16x16x32_bf16 v[10:13], v[178:181], v[220:223], v[10:13]
	v_mfma_f32_16x16x32_bf16 v[6:9], v[170:173], v[228:231], v[6:9]
	v_mfma_f32_16x16x32_bf16 v[2:5], v[178:181], v[228:231], v[2:5]
	s_setprio 0
	s_barrier
	s_add_i32 s49, s49, 2
	s_add_u32 s16, s16, 0x100
	s_addc_u32 s17, s17, 0
	s_add_u32 s47, s47, 0x100
	s_addc_u32 s48, s48, 0
